# GEMM K-loops: serpentine MFMA order on top of accumulator pairing (every adjacent MFMA shares an operand or the accumulator; half the accumulators add k=32..63 first)
# speedup vs baseline: 1.0181x; 1.0041x over previous
.LBB0_383:
	s_ashr_i32 s67, s66, 31
	s_lshl_b64 s[26:27], s[66:67], 19
	s_add_u32 s26, s40, s26
	s_addc_u32 s27, s41, s27
	s_and_b64 s[34:35], s[8:9], exec
	s_cselect_b32 s34, s27, s5
	s_cselect_b32 s35, s26, s4
	s_ashr_i32 s29, s28, 31
	s_lshl_b64 s[38:39], s[28:29], 19
	s_add_u32 s62, s10, s38
	s_addc_u32 s63, s11, s39
	s_and_b64 s[38:39], s[8:9], exec
	s_cselect_b32 s29, s63, s83
	s_cselect_b32 s38, s62, s82
	s_add_u32 s39, s82, 0x100
	s_addc_u32 s67, s83, 0
	s_mov_b32 s94, -2
	s_mov_b64 vcc, 0
	v_lshl_add_u64 v[132:133], s[4:5], 0, v[168:169]
	ds_read_b128 v[134:137], v199
	ds_read_b128 v[138:141], v200
	ds_read_b128 v[142:145], v201
	ds_read_b128 v[146:149], v202
	ds_read_b128 v[150:153], v203
	ds_read_b128 v[174:177], v204
	ds_read_b128 v[178:181], v205
	ds_read_b128 v[182:185], v206
	s_add_u32 s24, s4, vcc_lo
	s_addc_u32 s25, s5, vcc_hi
	s_add_u32 s24, s24, 0x100
	s_addc_u32 s25, s25, 0
	s_add_u32 s82, s39, vcc_lo
	s_addc_u32 s83, s67, vcc_hi
	s_cmpk_eq_i32 vcc_lo, 0x700
	s_cselect_b32 s87, s29, s83
	s_cselect_b32 s86, s38, s82
	s_cselect_b32 s83, s34, s25
	s_cselect_b32 s82, s35, s24
	v_lshl_add_u64 v[154:155], v[132:133], 0, vcc
	v_lshl_add_u64 v[250:251], v[154:155], 0, s[48:49]
	s_add_i32 m0, s79, 0x8000
	s_mov_b64 s[24:25], 0x20080
	ds_read_b128 v[218:221], v207
	ds_read_b128 v[222:225], v207 offset:2048
	ds_read_b128 v[226:229], v208
	ds_read_b128 v[230:233], v208 offset:2048
	ds_read_b128 v[234:237], v207 offset:4096
	ds_read_b128 v[238:241], v207 offset:6144
	ds_read_b128 v[242:245], v208 offset:4096
	ds_read_b128 v[246:249], v208 offset:6144
	global_load_lds_dwordx4 v[250:251], off
	v_lshl_add_u64 v[250:251], v[154:155], 0, s[24:25]
	s_add_i32 m0, s79, 0xa000
	s_mov_b64 s[24:25], 0x60080
	global_load_lds_dwordx4 v[250:251], off
	v_lshl_add_u64 v[250:251], v[154:155], 0, s[50:51]
	s_add_i32 m0, s79, 0xc000
	v_lshl_add_u64 v[154:155], v[154:155], 0, s[24:25]
	global_load_lds_dwordx4 v[250:251], off
	s_add_i32 m0, s79, 0xe000
	s_nop 0
	global_load_lds_dwordx4 v[154:155], off
	s_waitcnt lgkmcnt(0)
	s_barrier
	v_mfma_f32_16x16x32_bf16 v[128:131], v[134:137], v[218:221], 0
	v_mfma_f32_16x16x32_bf16 v[128:131], v[138:141], v[226:229], v[128:131]
	v_mfma_f32_16x16x32_bf16 v[124:127], v[142:145], v[218:221], 0
	v_mfma_f32_16x16x32_bf16 v[124:127], v[146:149], v[226:229], v[124:127]
	v_mfma_f32_16x16x32_bf16 v[108:111], v[142:145], v[222:225], 0
	v_mfma_f32_16x16x32_bf16 v[108:111], v[146:149], v[230:233], v[108:111]
	v_mfma_f32_16x16x32_bf16 v[112:115], v[134:137], v[222:225], 0
	v_mfma_f32_16x16x32_bf16 v[112:115], v[138:141], v[230:233], v[112:115]
	v_mfma_f32_16x16x32_bf16 v[96:99], v[134:137], v[234:237], 0
	v_mfma_f32_16x16x32_bf16 v[96:99], v[138:141], v[242:245], v[96:99]
	v_mfma_f32_16x16x32_bf16 v[92:95], v[142:145], v[234:237], 0
	v_mfma_f32_16x16x32_bf16 v[92:95], v[146:149], v[242:245], v[92:95]
	v_mfma_f32_16x16x32_bf16 v[76:79], v[142:145], v[238:241], 0
	v_mfma_f32_16x16x32_bf16 v[76:79], v[146:149], v[246:249], v[76:79]
	v_mfma_f32_16x16x32_bf16 v[80:83], v[134:137], v[238:241], 0
	v_mfma_f32_16x16x32_bf16 v[80:83], v[138:141], v[246:249], v[80:83]
	v_mfma_f32_16x16x32_bf16 v[120:123], v[150:153], v[218:221], 0
	v_mfma_f32_16x16x32_bf16 v[120:123], v[174:177], v[226:229], v[120:123]
	v_mfma_f32_16x16x32_bf16 v[116:119], v[178:181], v[218:221], 0
	v_mfma_f32_16x16x32_bf16 v[116:119], v[182:185], v[226:229], v[116:119]
	v_mfma_f32_16x16x32_bf16 v[100:103], v[178:181], v[222:225], 0
	v_mfma_f32_16x16x32_bf16 v[100:103], v[182:185], v[230:233], v[100:103]
	v_mfma_f32_16x16x32_bf16 v[104:107], v[150:153], v[222:225], 0
	v_mfma_f32_16x16x32_bf16 v[104:107], v[174:177], v[230:233], v[104:107]
	v_mfma_f32_16x16x32_bf16 v[88:91], v[150:153], v[234:237], 0
	v_mfma_f32_16x16x32_bf16 v[88:91], v[174:177], v[242:245], v[88:91]
	v_mfma_f32_16x16x32_bf16 v[84:87], v[178:181], v[234:237], 0
	v_mfma_f32_16x16x32_bf16 v[84:87], v[182:185], v[242:245], v[84:87]
	v_mfma_f32_16x16x32_bf16 v[68:71], v[178:181], v[238:241], 0
	v_mfma_f32_16x16x32_bf16 v[68:71], v[182:185], v[246:249], v[68:71]
	v_mfma_f32_16x16x32_bf16 v[72:75], v[150:153], v[238:241], 0
	v_mfma_f32_16x16x32_bf16 v[72:75], v[174:177], v[246:249], v[72:75]
	s_barrier
	s_add_i32 s24, s1, s77
	v_lshl_add_u64 v[154:155], s[86:87], 0, v[158:159]
	s_mov_b32 m0, s24
	ds_read_b128 v[218:221], v207 offset:16384
	ds_read_b128 v[222:225], v207 offset:18432
	ds_read_b128 v[226:229], v208 offset:16384
	ds_read_b128 v[230:233], v208 offset:18432
	ds_read_b128 v[234:237], v207 offset:20480
	ds_read_b128 v[238:241], v207 offset:22528
	ds_read_b128 v[242:245], v208 offset:20480
	ds_read_b128 v[246:249], v208 offset:22528
	global_load_lds_dwordx4 v[154:155], off
	v_lshl_add_u64 v[250:251], v[154:155], 0, s[14:15]
	s_add_i32 m0, s24, 0x2000
	s_add_i32 s24, s12, s77
	global_load_lds_dwordx4 v[250:251], off
	v_lshl_add_u64 v[250:251], v[154:155], 0, s[16:17]
	s_mov_b32 m0, s24
	s_nop 0
	global_load_lds_dwordx4 v[250:251], off
	v_lshl_add_u64 v[250:251], v[154:155], 0, s[18:19]
	s_add_i32 m0, s24, 0x2000
	s_nop 0
	global_load_lds_dwordx4 v[250:251], off
	s_waitcnt vmcnt(4)
	s_waitcnt lgkmcnt(0)
	s_barrier
	v_mfma_f32_16x16x32_bf16 v[64:67], v[134:137], v[218:221], 0
	v_mfma_f32_16x16x32_bf16 v[64:67], v[138:141], v[226:229], v[64:67]
	v_mfma_f32_16x16x32_bf16 v[60:63], v[142:145], v[218:221], 0
	v_mfma_f32_16x16x32_bf16 v[60:63], v[146:149], v[226:229], v[60:63]
	v_mfma_f32_16x16x32_bf16 v[44:47], v[142:145], v[222:225], 0
	v_mfma_f32_16x16x32_bf16 v[44:47], v[146:149], v[230:233], v[44:47]
	v_mfma_f32_16x16x32_bf16 v[48:51], v[134:137], v[222:225], 0
	v_mfma_f32_16x16x32_bf16 v[48:51], v[138:141], v[230:233], v[48:51]
	v_mfma_f32_16x16x32_bf16 v[32:35], v[134:137], v[234:237], 0
	v_mfma_f32_16x16x32_bf16 v[32:35], v[138:141], v[242:245], v[32:35]
	v_mfma_f32_16x16x32_bf16 v[28:31], v[142:145], v[234:237], 0
	v_mfma_f32_16x16x32_bf16 v[28:31], v[146:149], v[242:245], v[28:31]
	v_mfma_f32_16x16x32_bf16 v[12:15], v[142:145], v[238:241], 0
	v_mfma_f32_16x16x32_bf16 v[12:15], v[146:149], v[246:249], v[12:15]
	v_mfma_f32_16x16x32_bf16 v[16:19], v[134:137], v[238:241], 0
	v_mfma_f32_16x16x32_bf16 v[16:19], v[138:141], v[246:249], v[16:19]
	v_mfma_f32_16x16x32_bf16 v[56:59], v[150:153], v[218:221], 0
	v_mfma_f32_16x16x32_bf16 v[56:59], v[174:177], v[226:229], v[56:59]
	v_mfma_f32_16x16x32_bf16 v[52:55], v[178:181], v[218:221], 0
	v_mfma_f32_16x16x32_bf16 v[52:55], v[182:185], v[226:229], v[52:55]
	v_mfma_f32_16x16x32_bf16 v[36:39], v[178:181], v[222:225], 0
	v_mfma_f32_16x16x32_bf16 v[36:39], v[182:185], v[230:233], v[36:39]
	v_mfma_f32_16x16x32_bf16 v[40:43], v[150:153], v[222:225], 0
	v_mfma_f32_16x16x32_bf16 v[40:43], v[174:177], v[230:233], v[40:43]
	v_mfma_f32_16x16x32_bf16 v[24:27], v[150:153], v[234:237], 0
	v_mfma_f32_16x16x32_bf16 v[24:27], v[174:177], v[242:245], v[24:27]
	v_mfma_f32_16x16x32_bf16 v[20:23], v[178:181], v[234:237], 0
	v_mfma_f32_16x16x32_bf16 v[20:23], v[182:185], v[242:245], v[20:23]
	v_mfma_f32_16x16x32_bf16 v[4:7], v[178:181], v[238:241], 0
	v_mfma_f32_16x16x32_bf16 v[4:7], v[182:185], v[246:249], v[4:7]
	v_mfma_f32_16x16x32_bf16 v[8:11], v[150:153], v[238:241], 0
	v_mfma_f32_16x16x32_bf16 v[8:11], v[174:177], v[246:249], v[8:11]
	s_barrier
	ds_read_b128 v[134:137], v213
	ds_read_b128 v[138:141], v214
	ds_read_b128 v[142:145], v209
	ds_read_b128 v[146:149], v210
	ds_read_b128 v[150:153], v215
	ds_read_b128 v[174:177], v216
	ds_read_b128 v[178:181], v211
	ds_read_b128 v[182:185], v212
	s_mov_b32 m0, s79
	v_lshl_add_u64 v[250:251], s[82:83], 0, v[0:1]
	ds_read_b128 v[218:221], v207 offset:32768
	ds_read_b128 v[222:225], v207 offset:34816
	ds_read_b128 v[226:229], v208 offset:32768
	ds_read_b128 v[230:233], v208 offset:34816
	ds_read_b128 v[234:237], v207 offset:36864
	ds_read_b128 v[238:241], v207 offset:38912
	ds_read_b128 v[242:245], v208 offset:36864
	ds_read_b128 v[246:249], v208 offset:38912
	global_load_lds_dwordx4 v[250:251], off
	v_lshl_add_u64 v[252:253], v[250:251], 0, s[20:21]
	s_mov_b32 m0, s81
	s_nop 0
	global_load_lds_dwordx4 v[252:253], off
	v_lshl_add_u64 v[252:253], v[250:251], 0, s[14:15]
	s_mov_b32 m0, s97
	v_lshl_add_u64 v[250:251], v[250:251], 0, s[22:23]
	global_load_lds_dwordx4 v[252:253], off
	s_mov_b32 m0, s64
	s_nop 0
	global_load_lds_dwordx4 v[250:251], off
	s_waitcnt vmcnt(8)
	s_waitcnt lgkmcnt(0)
	s_barrier
	v_mfma_f32_16x16x32_bf16 v[128:131], v[134:137], v[218:221], v[128:131]
	v_mfma_f32_16x16x32_bf16 v[128:131], v[138:141], v[226:229], v[128:131]
	v_mfma_f32_16x16x32_bf16 v[124:127], v[146:149], v[226:229], v[124:127]
	v_mfma_f32_16x16x32_bf16 v[124:127], v[142:145], v[218:221], v[124:127]
	v_mfma_f32_16x16x32_bf16 v[108:111], v[142:145], v[222:225], v[108:111]
	v_mfma_f32_16x16x32_bf16 v[108:111], v[146:149], v[230:233], v[108:111]
	v_mfma_f32_16x16x32_bf16 v[112:115], v[138:141], v[230:233], v[112:115]
	v_mfma_f32_16x16x32_bf16 v[112:115], v[134:137], v[222:225], v[112:115]
	v_mfma_f32_16x16x32_bf16 v[96:99], v[134:137], v[234:237], v[96:99]
	v_mfma_f32_16x16x32_bf16 v[96:99], v[138:141], v[242:245], v[96:99]
	v_mfma_f32_16x16x32_bf16 v[92:95], v[146:149], v[242:245], v[92:95]
	v_mfma_f32_16x16x32_bf16 v[92:95], v[142:145], v[234:237], v[92:95]
	v_mfma_f32_16x16x32_bf16 v[76:79], v[142:145], v[238:241], v[76:79]
	v_mfma_f32_16x16x32_bf16 v[76:79], v[146:149], v[246:249], v[76:79]
	v_mfma_f32_16x16x32_bf16 v[80:83], v[138:141], v[246:249], v[80:83]
	v_mfma_f32_16x16x32_bf16 v[80:83], v[134:137], v[238:241], v[80:83]
	v_mfma_f32_16x16x32_bf16 v[120:123], v[150:153], v[218:221], v[120:123]
	v_mfma_f32_16x16x32_bf16 v[120:123], v[174:177], v[226:229], v[120:123]
	v_mfma_f32_16x16x32_bf16 v[116:119], v[182:185], v[226:229], v[116:119]
	v_mfma_f32_16x16x32_bf16 v[116:119], v[178:181], v[218:221], v[116:119]
	v_mfma_f32_16x16x32_bf16 v[100:103], v[178:181], v[222:225], v[100:103]
	v_mfma_f32_16x16x32_bf16 v[100:103], v[182:185], v[230:233], v[100:103]
	v_mfma_f32_16x16x32_bf16 v[104:107], v[174:177], v[230:233], v[104:107]
	v_mfma_f32_16x16x32_bf16 v[104:107], v[150:153], v[222:225], v[104:107]
	v_mfma_f32_16x16x32_bf16 v[88:91], v[150:153], v[234:237], v[88:91]
	v_mfma_f32_16x16x32_bf16 v[88:91], v[174:177], v[242:245], v[88:91]
	v_mfma_f32_16x16x32_bf16 v[84:87], v[182:185], v[242:245], v[84:87]
	v_mfma_f32_16x16x32_bf16 v[84:87], v[178:181], v[234:237], v[84:87]
	v_mfma_f32_16x16x32_bf16 v[68:71], v[178:181], v[238:241], v[68:71]
	v_mfma_f32_16x16x32_bf16 v[68:71], v[182:185], v[246:249], v[68:71]
	v_mfma_f32_16x16x32_bf16 v[72:75], v[174:177], v[246:249], v[72:75]
	v_mfma_f32_16x16x32_bf16 v[72:75], v[150:153], v[238:241], v[72:75]
	s_barrier
	s_add_i32 s24, s70, s77
	v_lshl_add_u64 v[250:251], v[154:155], 0, s[48:49]
	s_mov_b32 m0, s24
	ds_read_b128 v[218:221], v207 offset:49152
	ds_read_b128 v[222:225], v207 offset:51200
	ds_read_b128 v[226:229], v208 offset:49152
	ds_read_b128 v[230:233], v208 offset:51200
	ds_read_b128 v[234:237], v207 offset:53248
	ds_read_b128 v[238:241], v207 offset:55296
	ds_read_b128 v[242:245], v208 offset:53248
	ds_read_b128 v[246:249], v208 offset:55296
	global_load_lds_dwordx4 v[250:251], off
	v_lshl_add_u64 v[250:251], v[154:155], 0, s[50:51]
	s_add_i32 m0, s24, 0x2000
	s_add_i32 s24, s71, s77
	global_load_lds_dwordx4 v[250:251], off
	v_lshl_add_u64 v[250:251], v[154:155], 0, s[52:53]
	s_mov_b32 m0, s24
	v_lshl_add_u64 v[154:155], v[154:155], 0, s[54:55]
	global_load_lds_dwordx4 v[250:251], off
	s_add_i32 m0, s24, 0x2000
	s_nop 0
	global_load_lds_dwordx4 v[154:155], off
	s_waitcnt vmcnt(4)
	s_waitcnt lgkmcnt(0)
	s_barrier
	v_mfma_f32_16x16x32_bf16 v[64:67], v[134:137], v[218:221], v[64:67]
	v_mfma_f32_16x16x32_bf16 v[64:67], v[138:141], v[226:229], v[64:67]
	v_mfma_f32_16x16x32_bf16 v[60:63], v[146:149], v[226:229], v[60:63]
	v_mfma_f32_16x16x32_bf16 v[60:63], v[142:145], v[218:221], v[60:63]
	v_mfma_f32_16x16x32_bf16 v[44:47], v[142:145], v[222:225], v[44:47]
	v_mfma_f32_16x16x32_bf16 v[44:47], v[146:149], v[230:233], v[44:47]
	v_mfma_f32_16x16x32_bf16 v[48:51], v[138:141], v[230:233], v[48:51]
	v_mfma_f32_16x16x32_bf16 v[48:51], v[134:137], v[222:225], v[48:51]
	v_mfma_f32_16x16x32_bf16 v[32:35], v[134:137], v[234:237], v[32:35]
	v_mfma_f32_16x16x32_bf16 v[32:35], v[138:141], v[242:245], v[32:35]
	v_mfma_f32_16x16x32_bf16 v[28:31], v[146:149], v[242:245], v[28:31]
	v_mfma_f32_16x16x32_bf16 v[28:31], v[142:145], v[234:237], v[28:31]
	v_mfma_f32_16x16x32_bf16 v[12:15], v[142:145], v[238:241], v[12:15]
	v_mfma_f32_16x16x32_bf16 v[12:15], v[146:149], v[246:249], v[12:15]
	v_mfma_f32_16x16x32_bf16 v[16:19], v[138:141], v[246:249], v[16:19]
	v_mfma_f32_16x16x32_bf16 v[16:19], v[134:137], v[238:241], v[16:19]
	v_mfma_f32_16x16x32_bf16 v[56:59], v[150:153], v[218:221], v[56:59]
	v_mfma_f32_16x16x32_bf16 v[56:59], v[174:177], v[226:229], v[56:59]
	v_mfma_f32_16x16x32_bf16 v[52:55], v[182:185], v[226:229], v[52:55]
	v_mfma_f32_16x16x32_bf16 v[52:55], v[178:181], v[218:221], v[52:55]
	v_mfma_f32_16x16x32_bf16 v[36:39], v[178:181], v[222:225], v[36:39]
	v_mfma_f32_16x16x32_bf16 v[36:39], v[182:185], v[230:233], v[36:39]
	v_mfma_f32_16x16x32_bf16 v[40:43], v[174:177], v[230:233], v[40:43]
	v_mfma_f32_16x16x32_bf16 v[40:43], v[150:153], v[222:225], v[40:43]
	v_mfma_f32_16x16x32_bf16 v[24:27], v[150:153], v[234:237], v[24:27]
	v_mfma_f32_16x16x32_bf16 v[24:27], v[174:177], v[242:245], v[24:27]
	v_mfma_f32_16x16x32_bf16 v[20:23], v[182:185], v[242:245], v[20:23]
	v_mfma_f32_16x16x32_bf16 v[20:23], v[178:181], v[234:237], v[20:23]
	v_mfma_f32_16x16x32_bf16 v[4:7], v[178:181], v[238:241], v[4:7]
	v_mfma_f32_16x16x32_bf16 v[4:7], v[182:185], v[246:249], v[4:7]
	v_mfma_f32_16x16x32_bf16 v[8:11], v[174:177], v[246:249], v[8:11]
	v_mfma_f32_16x16x32_bf16 v[8:11], v[150:153], v[238:241], v[8:11]
	s_barrier
	s_add_i32 s94, s94, 2
	s_add_u32 vcc_lo, vcc_lo, 0x100
	s_addc_u32 vcc_hi, vcc_hi, 0
	s_cmp_gt_u32 s94, 13
.LBB0_384:
	ds_read_b128 v[134:137], v199
	ds_read_b128 v[138:141], v200
	ds_read_b128 v[142:145], v201
	ds_read_b128 v[146:149], v202
	ds_read_b128 v[150:153], v203
	ds_read_b128 v[174:177], v204
	ds_read_b128 v[178:181], v205
	ds_read_b128 v[182:185], v206
	s_add_u32 s24, s4, vcc_lo
	s_addc_u32 s25, s5, vcc_hi
	s_add_u32 s24, s24, 0x100
	s_addc_u32 s25, s25, 0
	s_add_u32 s82, s39, vcc_lo
	s_addc_u32 s83, s67, vcc_hi
	s_cmpk_eq_i32 vcc_lo, 0x700
	s_cselect_b32 s87, s29, s83
	s_cselect_b32 s86, s38, s82
	s_cselect_b32 s83, s34, s25
	s_cselect_b32 s82, s35, s24
	v_lshl_add_u64 v[154:155], v[132:133], 0, vcc
	v_lshl_add_u64 v[250:251], v[154:155], 0, s[48:49]
	s_add_i32 m0, s79, 0x8000
	s_mov_b64 s[24:25], 0x20080
	ds_read_b128 v[218:221], v207
	ds_read_b128 v[222:225], v207 offset:2048
	ds_read_b128 v[226:229], v208
	ds_read_b128 v[230:233], v208 offset:2048
	ds_read_b128 v[234:237], v207 offset:4096
	ds_read_b128 v[238:241], v207 offset:6144
	ds_read_b128 v[242:245], v208 offset:4096
	ds_read_b128 v[246:249], v208 offset:6144
	global_load_lds_dwordx4 v[250:251], off
	v_lshl_add_u64 v[250:251], v[154:155], 0, s[24:25]
	s_add_i32 m0, s79, 0xa000
	s_mov_b64 s[24:25], 0x60080
	global_load_lds_dwordx4 v[250:251], off
	v_lshl_add_u64 v[250:251], v[154:155], 0, s[50:51]
	s_add_i32 m0, s79, 0xc000
	v_lshl_add_u64 v[154:155], v[154:155], 0, s[24:25]
	global_load_lds_dwordx4 v[250:251], off
	s_add_i32 m0, s79, 0xe000
	s_nop 0
	global_load_lds_dwordx4 v[154:155], off
	s_waitcnt vmcnt(8)
	s_waitcnt lgkmcnt(0)
	s_barrier
	v_mfma_f32_16x16x32_bf16 v[128:131], v[134:137], v[218:221], v[128:131]
	v_mfma_f32_16x16x32_bf16 v[128:131], v[138:141], v[226:229], v[128:131]
	v_mfma_f32_16x16x32_bf16 v[124:127], v[146:149], v[226:229], v[124:127]
	v_mfma_f32_16x16x32_bf16 v[124:127], v[142:145], v[218:221], v[124:127]
	v_mfma_f32_16x16x32_bf16 v[108:111], v[142:145], v[222:225], v[108:111]
	v_mfma_f32_16x16x32_bf16 v[108:111], v[146:149], v[230:233], v[108:111]
	v_mfma_f32_16x16x32_bf16 v[112:115], v[138:141], v[230:233], v[112:115]
	v_mfma_f32_16x16x32_bf16 v[112:115], v[134:137], v[222:225], v[112:115]
	v_mfma_f32_16x16x32_bf16 v[96:99], v[134:137], v[234:237], v[96:99]
	v_mfma_f32_16x16x32_bf16 v[96:99], v[138:141], v[242:245], v[96:99]
	v_mfma_f32_16x16x32_bf16 v[92:95], v[146:149], v[242:245], v[92:95]
	v_mfma_f32_16x16x32_bf16 v[92:95], v[142:145], v[234:237], v[92:95]
	v_mfma_f32_16x16x32_bf16 v[76:79], v[142:145], v[238:241], v[76:79]
	v_mfma_f32_16x16x32_bf16 v[76:79], v[146:149], v[246:249], v[76:79]
	v_mfma_f32_16x16x32_bf16 v[80:83], v[138:141], v[246:249], v[80:83]
	v_mfma_f32_16x16x32_bf16 v[80:83], v[134:137], v[238:241], v[80:83]
	v_mfma_f32_16x16x32_bf16 v[120:123], v[150:153], v[218:221], v[120:123]
	v_mfma_f32_16x16x32_bf16 v[120:123], v[174:177], v[226:229], v[120:123]
	v_mfma_f32_16x16x32_bf16 v[116:119], v[182:185], v[226:229], v[116:119]
	v_mfma_f32_16x16x32_bf16 v[116:119], v[178:181], v[218:221], v[116:119]
	v_mfma_f32_16x16x32_bf16 v[100:103], v[178:181], v[222:225], v[100:103]
	v_mfma_f32_16x16x32_bf16 v[100:103], v[182:185], v[230:233], v[100:103]
	v_mfma_f32_16x16x32_bf16 v[104:107], v[174:177], v[230:233], v[104:107]
	v_mfma_f32_16x16x32_bf16 v[104:107], v[150:153], v[222:225], v[104:107]
	v_mfma_f32_16x16x32_bf16 v[88:91], v[150:153], v[234:237], v[88:91]
	v_mfma_f32_16x16x32_bf16 v[88:91], v[174:177], v[242:245], v[88:91]
	v_mfma_f32_16x16x32_bf16 v[84:87], v[182:185], v[242:245], v[84:87]
	v_mfma_f32_16x16x32_bf16 v[84:87], v[178:181], v[234:237], v[84:87]
	v_mfma_f32_16x16x32_bf16 v[68:71], v[178:181], v[238:241], v[68:71]
	v_mfma_f32_16x16x32_bf16 v[68:71], v[182:185], v[246:249], v[68:71]
	v_mfma_f32_16x16x32_bf16 v[72:75], v[174:177], v[246:249], v[72:75]
	v_mfma_f32_16x16x32_bf16 v[72:75], v[150:153], v[238:241], v[72:75]
	s_barrier
	s_add_i32 s24, s1, s77
	v_lshl_add_u64 v[154:155], s[86:87], 0, v[158:159]
	s_mov_b32 m0, s24
	ds_read_b128 v[218:221], v207 offset:16384
	ds_read_b128 v[222:225], v207 offset:18432
	ds_read_b128 v[226:229], v208 offset:16384
	ds_read_b128 v[230:233], v208 offset:18432
	ds_read_b128 v[234:237], v207 offset:20480
	ds_read_b128 v[238:241], v207 offset:22528
	ds_read_b128 v[242:245], v208 offset:20480
	ds_read_b128 v[246:249], v208 offset:22528
	global_load_lds_dwordx4 v[154:155], off
	v_lshl_add_u64 v[250:251], v[154:155], 0, s[14:15]
	s_add_i32 m0, s24, 0x2000
	s_add_i32 s24, s12, s77
	global_load_lds_dwordx4 v[250:251], off
	v_lshl_add_u64 v[250:251], v[154:155], 0, s[16:17]
	s_mov_b32 m0, s24
	s_nop 0
	global_load_lds_dwordx4 v[250:251], off
	v_lshl_add_u64 v[250:251], v[154:155], 0, s[18:19]
	s_add_i32 m0, s24, 0x2000
	s_nop 0
	global_load_lds_dwordx4 v[250:251], off
	s_waitcnt vmcnt(4)
	s_waitcnt lgkmcnt(0)
	s_barrier
	v_mfma_f32_16x16x32_bf16 v[64:67], v[134:137], v[218:221], v[64:67]
	v_mfma_f32_16x16x32_bf16 v[64:67], v[138:141], v[226:229], v[64:67]
	v_mfma_f32_16x16x32_bf16 v[60:63], v[146:149], v[226:229], v[60:63]
	v_mfma_f32_16x16x32_bf16 v[60:63], v[142:145], v[218:221], v[60:63]
	v_mfma_f32_16x16x32_bf16 v[44:47], v[142:145], v[222:225], v[44:47]
	v_mfma_f32_16x16x32_bf16 v[44:47], v[146:149], v[230:233], v[44:47]
	v_mfma_f32_16x16x32_bf16 v[48:51], v[138:141], v[230:233], v[48:51]
	v_mfma_f32_16x16x32_bf16 v[48:51], v[134:137], v[222:225], v[48:51]
	v_mfma_f32_16x16x32_bf16 v[32:35], v[134:137], v[234:237], v[32:35]
	v_mfma_f32_16x16x32_bf16 v[32:35], v[138:141], v[242:245], v[32:35]
	v_mfma_f32_16x16x32_bf16 v[28:31], v[146:149], v[242:245], v[28:31]
	v_mfma_f32_16x16x32_bf16 v[28:31], v[142:145], v[234:237], v[28:31]
	v_mfma_f32_16x16x32_bf16 v[12:15], v[142:145], v[238:241], v[12:15]
	v_mfma_f32_16x16x32_bf16 v[12:15], v[146:149], v[246:249], v[12:15]
	v_mfma_f32_16x16x32_bf16 v[16:19], v[138:141], v[246:249], v[16:19]
	v_mfma_f32_16x16x32_bf16 v[16:19], v[134:137], v[238:241], v[16:19]
	v_mfma_f32_16x16x32_bf16 v[56:59], v[150:153], v[218:221], v[56:59]
	v_mfma_f32_16x16x32_bf16 v[56:59], v[174:177], v[226:229], v[56:59]
	v_mfma_f32_16x16x32_bf16 v[52:55], v[182:185], v[226:229], v[52:55]
	v_mfma_f32_16x16x32_bf16 v[52:55], v[178:181], v[218:221], v[52:55]
	v_mfma_f32_16x16x32_bf16 v[36:39], v[178:181], v[222:225], v[36:39]
	v_mfma_f32_16x16x32_bf16 v[36:39], v[182:185], v[230:233], v[36:39]
	v_mfma_f32_16x16x32_bf16 v[40:43], v[174:177], v[230:233], v[40:43]
	v_mfma_f32_16x16x32_bf16 v[40:43], v[150:153], v[222:225], v[40:43]
	v_mfma_f32_16x16x32_bf16 v[24:27], v[150:153], v[234:237], v[24:27]
	v_mfma_f32_16x16x32_bf16 v[24:27], v[174:177], v[242:245], v[24:27]
	v_mfma_f32_16x16x32_bf16 v[20:23], v[182:185], v[242:245], v[20:23]
	v_mfma_f32_16x16x32_bf16 v[20:23], v[178:181], v[234:237], v[20:23]
	v_mfma_f32_16x16x32_bf16 v[4:7], v[178:181], v[238:241], v[4:7]
	v_mfma_f32_16x16x32_bf16 v[4:7], v[182:185], v[246:249], v[4:7]
	v_mfma_f32_16x16x32_bf16 v[8:11], v[174:177], v[246:249], v[8:11]
	v_mfma_f32_16x16x32_bf16 v[8:11], v[150:153], v[238:241], v[8:11]
	s_barrier
	ds_read_b128 v[134:137], v213
	ds_read_b128 v[138:141], v214
	ds_read_b128 v[142:145], v209
	ds_read_b128 v[146:149], v210
	ds_read_b128 v[150:153], v215
	ds_read_b128 v[174:177], v216
	ds_read_b128 v[178:181], v211
	ds_read_b128 v[182:185], v212
	s_mov_b32 m0, s79
	v_lshl_add_u64 v[250:251], s[82:83], 0, v[0:1]
	ds_read_b128 v[218:221], v207 offset:32768
	ds_read_b128 v[222:225], v207 offset:34816
	ds_read_b128 v[226:229], v208 offset:32768
	ds_read_b128 v[230:233], v208 offset:34816
	ds_read_b128 v[234:237], v207 offset:36864
	ds_read_b128 v[238:241], v207 offset:38912
	ds_read_b128 v[242:245], v208 offset:36864
	ds_read_b128 v[246:249], v208 offset:38912
	global_load_lds_dwordx4 v[250:251], off
	v_lshl_add_u64 v[252:253], v[250:251], 0, s[20:21]
	s_mov_b32 m0, s81
	s_nop 0
	global_load_lds_dwordx4 v[252:253], off
	v_lshl_add_u64 v[252:253], v[250:251], 0, s[14:15]
	s_mov_b32 m0, s97
	v_lshl_add_u64 v[250:251], v[250:251], 0, s[22:23]
	global_load_lds_dwordx4 v[252:253], off
	s_mov_b32 m0, s64
	s_nop 0
	global_load_lds_dwordx4 v[250:251], off
	s_waitcnt vmcnt(8)
	s_waitcnt lgkmcnt(0)
	s_barrier
	v_mfma_f32_16x16x32_bf16 v[128:131], v[134:137], v[218:221], v[128:131]
	v_mfma_f32_16x16x32_bf16 v[128:131], v[138:141], v[226:229], v[128:131]
	v_mfma_f32_16x16x32_bf16 v[124:127], v[146:149], v[226:229], v[124:127]
	v_mfma_f32_16x16x32_bf16 v[124:127], v[142:145], v[218:221], v[124:127]
	v_mfma_f32_16x16x32_bf16 v[108:111], v[142:145], v[222:225], v[108:111]
	v_mfma_f32_16x16x32_bf16 v[108:111], v[146:149], v[230:233], v[108:111]
	v_mfma_f32_16x16x32_bf16 v[112:115], v[138:141], v[230:233], v[112:115]
	v_mfma_f32_16x16x32_bf16 v[112:115], v[134:137], v[222:225], v[112:115]
	v_mfma_f32_16x16x32_bf16 v[96:99], v[134:137], v[234:237], v[96:99]
	v_mfma_f32_16x16x32_bf16 v[96:99], v[138:141], v[242:245], v[96:99]
	v_mfma_f32_16x16x32_bf16 v[92:95], v[146:149], v[242:245], v[92:95]
	v_mfma_f32_16x16x32_bf16 v[92:95], v[142:145], v[234:237], v[92:95]
	v_mfma_f32_16x16x32_bf16 v[76:79], v[142:145], v[238:241], v[76:79]
	v_mfma_f32_16x16x32_bf16 v[76:79], v[146:149], v[246:249], v[76:79]
	v_mfma_f32_16x16x32_bf16 v[80:83], v[138:141], v[246:249], v[80:83]
	v_mfma_f32_16x16x32_bf16 v[80:83], v[134:137], v[238:241], v[80:83]
	v_mfma_f32_16x16x32_bf16 v[120:123], v[150:153], v[218:221], v[120:123]
	v_mfma_f32_16x16x32_bf16 v[120:123], v[174:177], v[226:229], v[120:123]
	v_mfma_f32_16x16x32_bf16 v[116:119], v[182:185], v[226:229], v[116:119]
	v_mfma_f32_16x16x32_bf16 v[116:119], v[178:181], v[218:221], v[116:119]
	v_mfma_f32_16x16x32_bf16 v[100:103], v[178:181], v[222:225], v[100:103]
	v_mfma_f32_16x16x32_bf16 v[100:103], v[182:185], v[230:233], v[100:103]
	v_mfma_f32_16x16x32_bf16 v[104:107], v[174:177], v[230:233], v[104:107]
	v_mfma_f32_16x16x32_bf16 v[104:107], v[150:153], v[222:225], v[104:107]
	v_mfma_f32_16x16x32_bf16 v[88:91], v[150:153], v[234:237], v[88:91]
	v_mfma_f32_16x16x32_bf16 v[88:91], v[174:177], v[242:245], v[88:91]
	v_mfma_f32_16x16x32_bf16 v[84:87], v[182:185], v[242:245], v[84:87]
	v_mfma_f32_16x16x32_bf16 v[84:87], v[178:181], v[234:237], v[84:87]
	v_mfma_f32_16x16x32_bf16 v[68:71], v[178:181], v[238:241], v[68:71]
	v_mfma_f32_16x16x32_bf16 v[68:71], v[182:185], v[246:249], v[68:71]
	v_mfma_f32_16x16x32_bf16 v[72:75], v[174:177], v[246:249], v[72:75]
	v_mfma_f32_16x16x32_bf16 v[72:75], v[150:153], v[238:241], v[72:75]
	s_barrier
	s_add_i32 s24, s70, s77
	v_lshl_add_u64 v[250:251], v[154:155], 0, s[48:49]
	s_mov_b32 m0, s24
	ds_read_b128 v[218:221], v207 offset:49152
	ds_read_b128 v[222:225], v207 offset:51200
	ds_read_b128 v[226:229], v208 offset:49152
	ds_read_b128 v[230:233], v208 offset:51200
	ds_read_b128 v[234:237], v207 offset:53248
	ds_read_b128 v[238:241], v207 offset:55296
	ds_read_b128 v[242:245], v208 offset:53248
	ds_read_b128 v[246:249], v208 offset:55296
	global_load_lds_dwordx4 v[250:251], off
	v_lshl_add_u64 v[250:251], v[154:155], 0, s[50:51]
	s_add_i32 m0, s24, 0x2000
	s_add_i32 s24, s71, s77
	global_load_lds_dwordx4 v[250:251], off
	v_lshl_add_u64 v[250:251], v[154:155], 0, s[52:53]
	s_mov_b32 m0, s24
	v_lshl_add_u64 v[154:155], v[154:155], 0, s[54:55]
	global_load_lds_dwordx4 v[250:251], off
	s_add_i32 m0, s24, 0x2000
	s_nop 0
	global_load_lds_dwordx4 v[154:155], off
	s_waitcnt vmcnt(4)
	s_waitcnt lgkmcnt(0)
	s_barrier
	v_mfma_f32_16x16x32_bf16 v[64:67], v[134:137], v[218:221], v[64:67]
	v_mfma_f32_16x16x32_bf16 v[64:67], v[138:141], v[226:229], v[64:67]
	v_mfma_f32_16x16x32_bf16 v[60:63], v[146:149], v[226:229], v[60:63]
	v_mfma_f32_16x16x32_bf16 v[60:63], v[142:145], v[218:221], v[60:63]
	v_mfma_f32_16x16x32_bf16 v[44:47], v[142:145], v[222:225], v[44:47]
	v_mfma_f32_16x16x32_bf16 v[44:47], v[146:149], v[230:233], v[44:47]
	v_mfma_f32_16x16x32_bf16 v[48:51], v[138:141], v[230:233], v[48:51]
	v_mfma_f32_16x16x32_bf16 v[48:51], v[134:137], v[222:225], v[48:51]
	v_mfma_f32_16x16x32_bf16 v[32:35], v[134:137], v[234:237], v[32:35]
	v_mfma_f32_16x16x32_bf16 v[32:35], v[138:141], v[242:245], v[32:35]
	v_mfma_f32_16x16x32_bf16 v[28:31], v[146:149], v[242:245], v[28:31]
	v_mfma_f32_16x16x32_bf16 v[28:31], v[142:145], v[234:237], v[28:31]
	v_mfma_f32_16x16x32_bf16 v[12:15], v[142:145], v[238:241], v[12:15]
	v_mfma_f32_16x16x32_bf16 v[12:15], v[146:149], v[246:249], v[12:15]
	v_mfma_f32_16x16x32_bf16 v[16:19], v[138:141], v[246:249], v[16:19]
	v_mfma_f32_16x16x32_bf16 v[16:19], v[134:137], v[238:241], v[16:19]
	v_mfma_f32_16x16x32_bf16 v[56:59], v[150:153], v[218:221], v[56:59]
	v_mfma_f32_16x16x32_bf16 v[56:59], v[174:177], v[226:229], v[56:59]
	v_mfma_f32_16x16x32_bf16 v[52:55], v[182:185], v[226:229], v[52:55]
	v_mfma_f32_16x16x32_bf16 v[52:55], v[178:181], v[218:221], v[52:55]
	v_mfma_f32_16x16x32_bf16 v[36:39], v[178:181], v[222:225], v[36:39]
	v_mfma_f32_16x16x32_bf16 v[36:39], v[182:185], v[230:233], v[36:39]
	v_mfma_f32_16x16x32_bf16 v[40:43], v[174:177], v[230:233], v[40:43]
	v_mfma_f32_16x16x32_bf16 v[40:43], v[150:153], v[222:225], v[40:43]
	v_mfma_f32_16x16x32_bf16 v[24:27], v[150:153], v[234:237], v[24:27]
	v_mfma_f32_16x16x32_bf16 v[24:27], v[174:177], v[242:245], v[24:27]
	v_mfma_f32_16x16x32_bf16 v[20:23], v[182:185], v[242:245], v[20:23]
	v_mfma_f32_16x16x32_bf16 v[20:23], v[178:181], v[234:237], v[20:23]
	v_mfma_f32_16x16x32_bf16 v[4:7], v[178:181], v[238:241], v[4:7]
	v_mfma_f32_16x16x32_bf16 v[4:7], v[182:185], v[246:249], v[4:7]
	v_mfma_f32_16x16x32_bf16 v[8:11], v[174:177], v[246:249], v[8:11]
	v_mfma_f32_16x16x32_bf16 v[8:11], v[150:153], v[238:241], v[8:11]
	s_barrier
	s_add_i32 s94, s94, 2
	s_add_u32 vcc_lo, vcc_lo, 0x100
	s_addc_u32 vcc_hi, vcc_hi, 0
	s_cmp_gt_u32 s94, 13
	s_cbranch_scc0 .LBB0_384
	s_and_b64 vcc, exec, s[56:57]
	s_cbranch_vccz .LBB0_387
	s_barrier

.LBB0_779:
	v_add_u32_e32 v4, s73, v159
	v_add_u32_e32 v6, s73, v173
	ds_read_b128 v[136:139], v4
	ds_read_b128 v[140:143], v6
	v_add_u32_e32 v4, s77, v159
	s_add_u32 s26, s28, s64
	v_add_u32_e32 v6, s77, v173
	ds_read_b128 v[180:183], v4
	ds_read_b128 v[196:199], v6
	v_add_u32_e32 v4, s79, v159
	s_addc_u32 s27, s29, s65
	v_add_u32_e32 v6, s79, v173
	ds_read_b128 v[200:203], v4
	ds_read_b128 v[204:207], v6
	v_add_u32_e32 v4, s80, v159
	s_add_u32 s26, s26, 0x100
	v_add_u32_e32 v6, s80, v173
	ds_read_b128 v[208:211], v4
	ds_read_b128 v[212:215], v6
	s_addc_u32 s27, s27, 0
	s_add_u32 s34, s93, s64
	s_addc_u32 s35, s94, s65
	s_cmpk_eq_i32 s64, 0xb00
	s_cselect_b32 s35, s63, s35
	s_cselect_b32 s34, s62, s34
	s_cselect_b32 s27, s1, s27
	s_cselect_b32 s26, s0, s26
	v_lshl_add_u64 v[6:7], v[170:171], 0, s[64:65]
	v_lshl_add_u64 v[184:185], v[6:7], 0, s[24:25]
	s_add_i32 m0, s66, 0x8000
	s_mov_b64 s[38:39], 0x30080
	ds_read_b128 v[216:219], v176
	ds_read_b128 v[220:223], v176 offset:2048
	ds_read_b128 v[224:227], v177
	ds_read_b128 v[228:231], v177 offset:2048
	ds_read_b128 v[232:235], v176 offset:4096
	ds_read_b128 v[236:239], v176 offset:6144
	ds_read_b128 v[240:243], v177 offset:4096
	ds_read_b128 v[244:247], v177 offset:6144
	global_load_lds_dwordx4 v[184:185], off
	v_lshl_add_u64 v[184:185], v[6:7], 0, s[38:39]
	s_add_i32 m0, s66, 0xa000
	s_mov_b64 s[38:39], 0x90080
	global_load_lds_dwordx4 v[184:185], off
	v_lshl_add_u64 v[184:185], v[6:7], 0, s[50:51]
	s_add_i32 m0, s66, 0xc000
	v_lshl_add_u64 v[6:7], v[6:7], 0, s[38:39]
	global_load_lds_dwordx4 v[184:185], off
	s_add_i32 m0, s66, 0xe000
	s_nop 0
	global_load_lds_dwordx4 v[6:7], off
	s_waitcnt vmcnt(8)
	s_waitcnt lgkmcnt(0)
	s_barrier
	v_mfma_f32_16x16x32_bf16 v[132:135], v[136:139], v[216:219], v[132:135]
	v_mfma_f32_16x16x32_bf16 v[132:135], v[140:143], v[224:227], v[132:135]
	v_mfma_f32_16x16x32_bf16 v[128:131], v[196:199], v[224:227], v[128:131]
	v_mfma_f32_16x16x32_bf16 v[128:131], v[180:183], v[216:219], v[128:131]
	v_mfma_f32_16x16x32_bf16 v[112:115], v[180:183], v[220:223], v[112:115]
	v_mfma_f32_16x16x32_bf16 v[112:115], v[196:199], v[228:231], v[112:115]
	v_mfma_f32_16x16x32_bf16 v[116:119], v[140:143], v[228:231], v[116:119]
	v_mfma_f32_16x16x32_bf16 v[116:119], v[136:139], v[220:223], v[116:119]
	v_mfma_f32_16x16x32_bf16 v[100:103], v[136:139], v[232:235], v[100:103]
	v_mfma_f32_16x16x32_bf16 v[100:103], v[140:143], v[240:243], v[100:103]
	v_mfma_f32_16x16x32_bf16 v[96:99], v[196:199], v[240:243], v[96:99]
	v_mfma_f32_16x16x32_bf16 v[96:99], v[180:183], v[232:235], v[96:99]
	v_mfma_f32_16x16x32_bf16 v[80:83], v[180:183], v[236:239], v[80:83]
	v_mfma_f32_16x16x32_bf16 v[80:83], v[196:199], v[244:247], v[80:83]
	v_mfma_f32_16x16x32_bf16 v[84:87], v[140:143], v[244:247], v[84:87]
	v_mfma_f32_16x16x32_bf16 v[84:87], v[136:139], v[236:239], v[84:87]
	v_mfma_f32_16x16x32_bf16 v[124:127], v[200:203], v[216:219], v[124:127]
	v_mfma_f32_16x16x32_bf16 v[124:127], v[204:207], v[224:227], v[124:127]
	v_mfma_f32_16x16x32_bf16 v[120:123], v[212:215], v[224:227], v[120:123]
	v_mfma_f32_16x16x32_bf16 v[120:123], v[208:211], v[216:219], v[120:123]
	v_mfma_f32_16x16x32_bf16 v[104:107], v[208:211], v[220:223], v[104:107]
	v_mfma_f32_16x16x32_bf16 v[104:107], v[212:215], v[228:231], v[104:107]
	v_mfma_f32_16x16x32_bf16 v[108:111], v[204:207], v[228:231], v[108:111]
	v_mfma_f32_16x16x32_bf16 v[108:111], v[200:203], v[220:223], v[108:111]
	v_mfma_f32_16x16x32_bf16 v[92:95], v[200:203], v[232:235], v[92:95]
	v_mfma_f32_16x16x32_bf16 v[92:95], v[204:207], v[240:243], v[92:95]
	v_mfma_f32_16x16x32_bf16 v[88:91], v[212:215], v[240:243], v[88:91]
	v_mfma_f32_16x16x32_bf16 v[88:91], v[208:211], v[232:235], v[88:91]
	v_mfma_f32_16x16x32_bf16 v[72:75], v[208:211], v[236:239], v[72:75]
	v_mfma_f32_16x16x32_bf16 v[72:75], v[212:215], v[244:247], v[72:75]
	v_mfma_f32_16x16x32_bf16 v[76:79], v[204:207], v[244:247], v[76:79]
	v_mfma_f32_16x16x32_bf16 v[76:79], v[200:203], v[236:239], v[76:79]
	s_barrier
	v_lshl_add_u64 v[184:185], s[34:35], 0, v[146:147]
	s_add_i32 s34, s73, s3
	s_mov_b32 m0, s34
	ds_read_b128 v[216:219], v176 offset:16384
	ds_read_b128 v[220:223], v176 offset:18432
	ds_read_b128 v[224:227], v177 offset:16384
	ds_read_b128 v[228:231], v177 offset:18432
	ds_read_b128 v[232:235], v176 offset:20480
	ds_read_b128 v[236:239], v176 offset:22528
	ds_read_b128 v[240:243], v177 offset:20480
	ds_read_b128 v[244:247], v177 offset:22528
	global_load_lds_dwordx4 v[184:185], off
	v_lshl_add_u64 v[6:7], v[184:185], 0, s[12:13]
	s_add_i32 m0, s34, 0x2000
	s_add_i32 s34, s79, s3
	global_load_lds_dwordx4 v[6:7], off
	v_lshl_add_u64 v[6:7], v[184:185], 0, s[14:15]
	s_mov_b32 m0, s34
	s_nop 0
	global_load_lds_dwordx4 v[6:7], off
	v_lshl_add_u64 v[6:7], v[184:185], 0, s[16:17]
	s_add_i32 m0, s34, 0x2000
	s_nop 0
	global_load_lds_dwordx4 v[6:7], off
	s_waitcnt vmcnt(4)
	s_waitcnt lgkmcnt(0)
	s_barrier
	v_mfma_f32_16x16x32_bf16 v[68:71], v[136:139], v[216:219], v[68:71]
	v_mfma_f32_16x16x32_bf16 v[68:71], v[140:143], v[224:227], v[68:71]
	v_mfma_f32_16x16x32_bf16 v[64:67], v[196:199], v[224:227], v[64:67]
	v_mfma_f32_16x16x32_bf16 v[64:67], v[180:183], v[216:219], v[64:67]
	v_mfma_f32_16x16x32_bf16 v[48:51], v[180:183], v[220:223], v[48:51]
	v_mfma_f32_16x16x32_bf16 v[48:51], v[196:199], v[228:231], v[48:51]
	v_mfma_f32_16x16x32_bf16 v[52:55], v[140:143], v[228:231], v[52:55]
	v_mfma_f32_16x16x32_bf16 v[52:55], v[136:139], v[220:223], v[52:55]
	v_mfma_f32_16x16x32_bf16 v[36:39], v[136:139], v[232:235], v[36:39]
	v_mfma_f32_16x16x32_bf16 v[36:39], v[140:143], v[240:243], v[36:39]
	v_mfma_f32_16x16x32_bf16 v[32:35], v[196:199], v[240:243], v[32:35]
	v_mfma_f32_16x16x32_bf16 v[32:35], v[180:183], v[232:235], v[32:35]
	v_mfma_f32_16x16x32_bf16 v[16:19], v[180:183], v[236:239], v[16:19]
	v_mfma_f32_16x16x32_bf16 v[16:19], v[196:199], v[244:247], v[16:19]
	v_mfma_f32_16x16x32_bf16 v[20:23], v[140:143], v[244:247], v[20:23]
	v_mfma_f32_16x16x32_bf16 v[20:23], v[136:139], v[236:239], v[20:23]
	v_mfma_f32_16x16x32_bf16 v[60:63], v[200:203], v[216:219], v[60:63]
	v_mfma_f32_16x16x32_bf16 v[60:63], v[204:207], v[224:227], v[60:63]
	v_mfma_f32_16x16x32_bf16 v[56:59], v[208:211], v[216:219], v[56:59]
	v_mfma_f32_16x16x32_bf16 v[56:59], v[212:215], v[224:227], v[56:59]
	v_mfma_f32_16x16x32_bf16 v[44:47], v[200:203], v[220:223], v[44:47]
	v_mfma_f32_16x16x32_bf16 v[44:47], v[204:207], v[228:231], v[44:47]
	v_mfma_f32_16x16x32_bf16 v[40:43], v[208:211], v[220:223], v[40:43]
	v_mfma_f32_16x16x32_bf16 v[40:43], v[212:215], v[228:231], v[40:43]
	v_mfma_f32_16x16x32_bf16 v[28:31], v[200:203], v[232:235], v[28:31]
	v_mfma_f32_16x16x32_bf16 v[28:31], v[204:207], v[240:243], v[28:31]
	v_mfma_f32_16x16x32_bf16 v[24:27], v[208:211], v[232:235], v[24:27]
	v_mfma_f32_16x16x32_bf16 v[24:27], v[212:215], v[240:243], v[24:27]
	v_mfma_f32_16x16x32_bf16 v[12:15], v[200:203], v[236:239], v[12:15]
	v_mfma_f32_16x16x32_bf16 v[12:15], v[204:207], v[244:247], v[12:15]
	v_mfma_f32_16x16x32_bf16 v[6:9], v[208:211], v[236:239], v[8:11]
	v_mfma_f32_16x16x32_bf16 v[6:9], v[212:215], v[244:247], v[6:9]
	s_barrier
	v_add_u32_e32 v4, s83, v159
	v_add_u32_e32 v10, s83, v173
	ds_read_b128 v[136:139], v4
	ds_read_b128 v[140:143], v10
	v_add_u32_e32 v4, s81, v159
	v_add_u32_e32 v10, s81, v173
	ds_read_b128 v[180:183], v4
	ds_read_b128 v[196:199], v10
	v_add_u32_e32 v4, s84, v159
	v_add_u32_e32 v10, s84, v173
	ds_read_b128 v[200:203], v4
	ds_read_b128 v[204:207], v10
	v_add_u32_e32 v4, s82, v159
	v_add_u32_e32 v10, s82, v173
	ds_read_b128 v[208:211], v4
	ds_read_b128 v[212:215], v10
	s_mov_b32 m0, s66
	v_lshl_add_u64 v[10:11], s[26:27], 0, v[144:145]
	ds_read_b128 v[216:219], v176 offset:32768
	ds_read_b128 v[220:223], v176 offset:34816
	ds_read_b128 v[224:227], v177 offset:32768
	ds_read_b128 v[228:231], v177 offset:34816
	ds_read_b128 v[232:235], v176 offset:36864
	ds_read_b128 v[236:239], v176 offset:38912
	ds_read_b128 v[240:243], v177 offset:36864
	ds_read_b128 v[244:247], v177 offset:38912
	global_load_lds_dwordx4 v[10:11], off
	v_lshl_add_u64 v[248:249], v[10:11], 0, s[18:19]
	s_mov_b32 m0, s67
	s_nop 0
	global_load_lds_dwordx4 v[248:249], off
	v_lshl_add_u64 v[248:249], v[10:11], 0, s[12:13]
	s_mov_b32 m0, s68
	v_lshl_add_u64 v[10:11], v[10:11], 0, s[20:21]
	global_load_lds_dwordx4 v[248:249], off
	s_mov_b32 m0, s69
	s_nop 0
	global_load_lds_dwordx4 v[10:11], off
	s_waitcnt vmcnt(8)
	s_waitcnt lgkmcnt(0)
	s_barrier
	v_mfma_f32_16x16x32_bf16 v[132:135], v[136:139], v[216:219], v[132:135]
	v_mfma_f32_16x16x32_bf16 v[132:135], v[140:143], v[224:227], v[132:135]
	v_mfma_f32_16x16x32_bf16 v[128:131], v[196:199], v[224:227], v[128:131]
	v_mfma_f32_16x16x32_bf16 v[128:131], v[180:183], v[216:219], v[128:131]
	v_mfma_f32_16x16x32_bf16 v[112:115], v[180:183], v[220:223], v[112:115]
	v_mfma_f32_16x16x32_bf16 v[112:115], v[196:199], v[228:231], v[112:115]
	v_mfma_f32_16x16x32_bf16 v[116:119], v[140:143], v[228:231], v[116:119]
	v_mfma_f32_16x16x32_bf16 v[116:119], v[136:139], v[220:223], v[116:119]
	v_mfma_f32_16x16x32_bf16 v[100:103], v[136:139], v[232:235], v[100:103]
	v_mfma_f32_16x16x32_bf16 v[100:103], v[140:143], v[240:243], v[100:103]
	v_mfma_f32_16x16x32_bf16 v[96:99], v[196:199], v[240:243], v[96:99]
	v_mfma_f32_16x16x32_bf16 v[96:99], v[180:183], v[232:235], v[96:99]
	v_mfma_f32_16x16x32_bf16 v[80:83], v[180:183], v[236:239], v[80:83]
	v_mfma_f32_16x16x32_bf16 v[80:83], v[196:199], v[244:247], v[80:83]
	v_mfma_f32_16x16x32_bf16 v[84:87], v[140:143], v[244:247], v[84:87]
	v_mfma_f32_16x16x32_bf16 v[84:87], v[136:139], v[236:239], v[84:87]
	v_mfma_f32_16x16x32_bf16 v[124:127], v[200:203], v[216:219], v[124:127]
	v_mfma_f32_16x16x32_bf16 v[124:127], v[204:207], v[224:227], v[124:127]
	v_mfma_f32_16x16x32_bf16 v[120:123], v[212:215], v[224:227], v[120:123]
	v_mfma_f32_16x16x32_bf16 v[120:123], v[208:211], v[216:219], v[120:123]
	v_mfma_f32_16x16x32_bf16 v[104:107], v[208:211], v[220:223], v[104:107]
	v_mfma_f32_16x16x32_bf16 v[104:107], v[212:215], v[228:231], v[104:107]
	v_mfma_f32_16x16x32_bf16 v[108:111], v[204:207], v[228:231], v[108:111]
	v_mfma_f32_16x16x32_bf16 v[108:111], v[200:203], v[220:223], v[108:111]
	v_mfma_f32_16x16x32_bf16 v[92:95], v[200:203], v[232:235], v[92:95]
	v_mfma_f32_16x16x32_bf16 v[92:95], v[204:207], v[240:243], v[92:95]
	v_mfma_f32_16x16x32_bf16 v[88:91], v[212:215], v[240:243], v[88:91]
	v_mfma_f32_16x16x32_bf16 v[88:91], v[208:211], v[232:235], v[88:91]
	v_mfma_f32_16x16x32_bf16 v[72:75], v[208:211], v[236:239], v[72:75]
	v_mfma_f32_16x16x32_bf16 v[72:75], v[212:215], v[244:247], v[72:75]
	v_mfma_f32_16x16x32_bf16 v[76:79], v[204:207], v[244:247], v[76:79]
	v_mfma_f32_16x16x32_bf16 v[76:79], v[200:203], v[236:239], v[76:79]
	s_barrier
	s_add_i32 s26, s83, s3
	v_lshl_add_u64 v[10:11], v[184:185], 0, s[24:25]
	s_mov_b32 m0, s26
	ds_read_b128 v[216:219], v176 offset:49152
	ds_read_b128 v[220:223], v176 offset:51200
	ds_read_b128 v[224:227], v177 offset:49152
	ds_read_b128 v[228:231], v177 offset:51200
	ds_read_b128 v[232:235], v176 offset:53248
	ds_read_b128 v[236:239], v176 offset:55296
	ds_read_b128 v[240:243], v177 offset:53248
	ds_read_b128 v[244:247], v177 offset:55296
	global_load_lds_dwordx4 v[10:11], off
	v_lshl_add_u64 v[10:11], v[184:185], 0, s[50:51]
	s_add_i32 m0, s26, 0x2000
	s_add_i32 s26, s84, s3
	global_load_lds_dwordx4 v[10:11], off
	v_lshl_add_u64 v[10:11], v[184:185], 0, s[52:53]
	s_mov_b32 m0, s26
	s_nop 0
	global_load_lds_dwordx4 v[10:11], off
	v_lshl_add_u64 v[10:11], v[184:185], 0, s[54:55]
	s_add_i32 m0, s26, 0x2000
	s_nop 0
	global_load_lds_dwordx4 v[10:11], off
	s_waitcnt vmcnt(4)
	s_waitcnt lgkmcnt(0)
	s_barrier
	v_mfma_f32_16x16x32_bf16 v[68:71], v[136:139], v[216:219], v[68:71]
	v_mfma_f32_16x16x32_bf16 v[68:71], v[140:143], v[224:227], v[68:71]
	v_mfma_f32_16x16x32_bf16 v[64:67], v[196:199], v[224:227], v[64:67]
	v_mfma_f32_16x16x32_bf16 v[64:67], v[180:183], v[216:219], v[64:67]
	v_mfma_f32_16x16x32_bf16 v[48:51], v[180:183], v[220:223], v[48:51]
	v_mfma_f32_16x16x32_bf16 v[48:51], v[196:199], v[228:231], v[48:51]
	v_mfma_f32_16x16x32_bf16 v[52:55], v[140:143], v[228:231], v[52:55]
	v_mfma_f32_16x16x32_bf16 v[52:55], v[136:139], v[220:223], v[52:55]
	v_mfma_f32_16x16x32_bf16 v[36:39], v[136:139], v[232:235], v[36:39]
	v_mfma_f32_16x16x32_bf16 v[36:39], v[140:143], v[240:243], v[36:39]
	v_mfma_f32_16x16x32_bf16 v[32:35], v[196:199], v[240:243], v[32:35]
	v_mfma_f32_16x16x32_bf16 v[32:35], v[180:183], v[232:235], v[32:35]
	v_mfma_f32_16x16x32_bf16 v[16:19], v[180:183], v[236:239], v[16:19]
	v_mfma_f32_16x16x32_bf16 v[16:19], v[196:199], v[244:247], v[16:19]
	v_mfma_f32_16x16x32_bf16 v[20:23], v[140:143], v[244:247], v[20:23]
	v_mfma_f32_16x16x32_bf16 v[20:23], v[136:139], v[236:239], v[20:23]
	v_mfma_f32_16x16x32_bf16 v[60:63], v[200:203], v[216:219], v[60:63]
	v_mfma_f32_16x16x32_bf16 v[60:63], v[204:207], v[224:227], v[60:63]
	v_mfma_f32_16x16x32_bf16 v[56:59], v[208:211], v[216:219], v[56:59]
	v_mfma_f32_16x16x32_bf16 v[56:59], v[212:215], v[224:227], v[56:59]
	v_mfma_f32_16x16x32_bf16 v[44:47], v[200:203], v[220:223], v[44:47]
	v_mfma_f32_16x16x32_bf16 v[44:47], v[204:207], v[228:231], v[44:47]
	v_mfma_f32_16x16x32_bf16 v[40:43], v[208:211], v[220:223], v[40:43]
	v_mfma_f32_16x16x32_bf16 v[40:43], v[212:215], v[228:231], v[40:43]
	v_mfma_f32_16x16x32_bf16 v[28:31], v[200:203], v[232:235], v[28:31]
	v_mfma_f32_16x16x32_bf16 v[28:31], v[204:207], v[240:243], v[28:31]
	v_mfma_f32_16x16x32_bf16 v[24:27], v[208:211], v[232:235], v[24:27]
	v_mfma_f32_16x16x32_bf16 v[24:27], v[212:215], v[240:243], v[24:27]
	v_mfma_f32_16x16x32_bf16 v[10:13], v[200:203], v[236:239], v[12:15]
	v_mfma_f32_16x16x32_bf16 v[12:15], v[204:207], v[244:247], v[10:13]
	v_mfma_f32_16x16x32_bf16 v[6:9], v[208:211], v[236:239], v[6:9]
	v_mfma_f32_16x16x32_bf16 v[8:11], v[212:215], v[244:247], v[6:9]
	s_barrier
	s_add_i32 s95, s95, 2
	s_add_u32 s64, s64, 0x100
	s_addc_u32 s65, s65, 0
	s_cmp_gt_u32 s95, 21
	s_cbranch_scc1 .LBB0_782

.LBB0_973:
	v_add_u32_e32 v133, s72, v163
	v_add_u32_e32 v140, s72, v164
	ds_read_b128 v[136:139], v133
	ds_read_b128 v[148:151], v140
	v_add_u32_e32 v133, s73, v163
	s_add_u32 s70, s28, s26
	v_add_u32_e32 v140, s73, v164
	s_waitcnt lgkmcnt(0)
	ds_read_b128 v[152:155], v133
	ds_read_b128 v[174:177], v140
	v_add_u32_e32 v133, s77, v163
	s_addc_u32 s71, s29, s27
	v_add_u32_e32 v140, s77, v164
	ds_read_b128 v[178:181], v133
	ds_read_b128 v[182:185], v140
	v_add_u32_e32 v133, s79, v163
	s_add_u32 s70, s70, 0x100
	v_add_u32_e32 v140, s79, v164
	ds_read_b128 v[196:199], v133
	ds_read_b128 v[200:203], v140
	s_addc_u32 s71, s71, 0
	s_add_u32 s86, s65, s26
	s_addc_u32 s87, s85, s27
	s_cmpk_eq_i32 s26, 0x700
	s_cselect_b32 s87, s61, s87
	s_cselect_b32 s86, s88, s86
	s_cselect_b32 s71, s54, s71
	s_cselect_b32 s70, s63, s70
	v_lshl_add_u64 v[140:141], v[134:135], 0, s[26:27]
	v_lshl_add_u64 v[160:161], v[140:141], 0, s[36:37]
	s_add_i32 m0, s5, 0x8000
	s_mov_b64 s[90:91], 0x20080
	ds_read_b128 v[204:207], v166
	ds_read_b128 v[208:211], v166 offset:2048
	ds_read_b128 v[212:215], v167
	ds_read_b128 v[216:219], v167 offset:2048
	ds_read_b128 v[220:223], v166 offset:4096
	ds_read_b128 v[224:227], v166 offset:6144
	ds_read_b128 v[228:231], v167 offset:4096
	ds_read_b128 v[232:235], v167 offset:6144
	global_load_lds_dwordx4 v[160:161], off
	v_lshl_add_u64 v[160:161], v[140:141], 0, s[90:91]
	s_add_i32 m0, s5, 0xa000
	s_mov_b64 s[90:91], 0x60080
	global_load_lds_dwordx4 v[160:161], off
	v_lshl_add_u64 v[160:161], v[140:141], 0, s[44:45]
	s_add_i32 m0, s5, 0xc000
	v_lshl_add_u64 v[140:141], v[140:141], 0, s[90:91]
	global_load_lds_dwordx4 v[160:161], off
	s_add_i32 m0, s5, 0xe000
	s_nop 0
	global_load_lds_dwordx4 v[140:141], off
	s_waitcnt vmcnt(8)
	s_waitcnt lgkmcnt(0)
	s_barrier
	v_mfma_f32_16x16x32_bf16 v[8:11], v[136:139], v[204:207], v[8:11]
	v_mfma_f32_16x16x32_bf16 v[8:11], v[148:151], v[212:215], v[8:11]
	v_mfma_f32_16x16x32_bf16 v[4:7], v[174:177], v[212:215], v[4:7]
	v_mfma_f32_16x16x32_bf16 v[4:7], v[152:155], v[204:207], v[4:7]
	v_mfma_f32_16x16x32_bf16 v[16:19], v[152:155], v[208:211], v[16:19]
	v_mfma_f32_16x16x32_bf16 v[16:19], v[174:177], v[216:219], v[16:19]
	v_mfma_f32_16x16x32_bf16 v[12:15], v[148:151], v[216:219], v[12:15]
	v_mfma_f32_16x16x32_bf16 v[12:15], v[136:139], v[208:211], v[12:15]
	v_mfma_f32_16x16x32_bf16 v[44:47], v[136:139], v[220:223], v[44:47]
	v_mfma_f32_16x16x32_bf16 v[44:47], v[148:151], v[228:231], v[44:47]
	v_mfma_f32_16x16x32_bf16 v[36:39], v[174:177], v[228:231], v[36:39]
	v_mfma_f32_16x16x32_bf16 v[36:39], v[152:155], v[220:223], v[36:39]
	v_mfma_f32_16x16x32_bf16 v[24:27], v[152:155], v[224:227], v[24:27]
	v_mfma_f32_16x16x32_bf16 v[24:27], v[174:177], v[232:235], v[24:27]
	v_mfma_f32_16x16x32_bf16 v[20:23], v[148:151], v[232:235], v[20:23]
	v_mfma_f32_16x16x32_bf16 v[20:23], v[136:139], v[224:227], v[20:23]
	v_mfma_f32_16x16x32_bf16 v[32:35], v[178:181], v[204:207], v[32:35]
	v_mfma_f32_16x16x32_bf16 v[32:35], v[182:185], v[212:215], v[32:35]
	v_mfma_f32_16x16x32_bf16 v[28:31], v[200:203], v[212:215], v[28:31]
	v_mfma_f32_16x16x32_bf16 v[28:31], v[196:199], v[204:207], v[28:31]
	v_mfma_f32_16x16x32_bf16 v[52:55], v[196:199], v[208:211], v[52:55]
	v_mfma_f32_16x16x32_bf16 v[52:55], v[200:203], v[216:219], v[52:55]
	v_mfma_f32_16x16x32_bf16 v[40:43], v[182:185], v[216:219], v[40:43]
	v_mfma_f32_16x16x32_bf16 v[40:43], v[178:181], v[208:211], v[40:43]
	v_mfma_f32_16x16x32_bf16 v[48:51], v[178:181], v[220:223], v[48:51]
	v_mfma_f32_16x16x32_bf16 v[48:51], v[182:185], v[228:231], v[48:51]
	v_mfma_f32_16x16x32_bf16 v[60:63], v[200:203], v[228:231], v[60:63]
	v_mfma_f32_16x16x32_bf16 v[60:63], v[196:199], v[220:223], v[60:63]
	v_mfma_f32_16x16x32_bf16 v[64:67], v[196:199], v[224:227], v[64:67]
	v_mfma_f32_16x16x32_bf16 v[64:67], v[200:203], v[232:235], v[64:67]
	v_mfma_f32_16x16x32_bf16 v[56:59], v[182:185], v[232:235], v[56:59]
	v_mfma_f32_16x16x32_bf16 v[56:59], v[178:181], v[224:227], v[56:59]
	s_barrier
	v_lshl_add_u64 v[140:141], s[86:87], 0, v[158:159]
	s_add_i32 s86, s72, s34
	s_mov_b32 m0, s86
	ds_read_b128 v[204:207], v166 offset:16384
	ds_read_b128 v[208:211], v166 offset:18432
	ds_read_b128 v[212:215], v167 offset:16384
	ds_read_b128 v[216:219], v167 offset:18432
	ds_read_b128 v[220:223], v166 offset:20480
	ds_read_b128 v[224:227], v166 offset:22528
	ds_read_b128 v[228:231], v167 offset:20480
	ds_read_b128 v[232:235], v167 offset:22528
	global_load_lds_dwordx4 v[140:141], off
	v_lshl_add_u64 v[160:161], v[140:141], 0, s[18:19]
	s_add_i32 m0, s86, 0x2000
	s_mov_b64 s[86:87], 0x10000
	global_load_lds_dwordx4 v[160:161], off
	v_lshl_add_u64 v[160:161], v[140:141], 0, s[86:87]
	s_add_i32 s86, s77, s34
	s_mov_b32 m0, s86
	s_nop 0
	global_load_lds_dwordx4 v[160:161], off
	v_lshl_add_u64 v[160:161], v[140:141], 0, s[20:21]
	s_add_i32 m0, s86, 0x2000
	s_nop 0
	global_load_lds_dwordx4 v[160:161], off
	s_waitcnt vmcnt(4)
	s_waitcnt lgkmcnt(0)
	s_barrier
	v_mfma_f32_16x16x32_bf16 v[68:71], v[136:139], v[204:207], v[68:71]
	v_mfma_f32_16x16x32_bf16 v[68:71], v[148:151], v[212:215], v[68:71]
	v_mfma_f32_16x16x32_bf16 v[72:75], v[174:177], v[212:215], v[72:75]
	v_mfma_f32_16x16x32_bf16 v[72:75], v[152:155], v[204:207], v[72:75]
	v_mfma_f32_16x16x32_bf16 v[84:87], v[152:155], v[208:211], v[84:87]
	v_mfma_f32_16x16x32_bf16 v[84:87], v[174:177], v[216:219], v[84:87]
	v_mfma_f32_16x16x32_bf16 v[92:95], v[148:151], v[216:219], v[92:95]
	v_mfma_f32_16x16x32_bf16 v[92:95], v[136:139], v[208:211], v[92:95]
	v_mfma_f32_16x16x32_bf16 v[76:79], v[136:139], v[220:223], v[76:79]
	v_mfma_f32_16x16x32_bf16 v[76:79], v[148:151], v[228:231], v[76:79]
	v_mfma_f32_16x16x32_bf16 v[80:83], v[174:177], v[228:231], v[80:83]
	v_mfma_f32_16x16x32_bf16 v[80:83], v[152:155], v[220:223], v[80:83]
	v_mfma_f32_16x16x32_bf16 v[108:111], v[152:155], v[224:227], v[108:111]
	v_mfma_f32_16x16x32_bf16 v[108:111], v[174:177], v[232:235], v[108:111]
	v_mfma_f32_16x16x32_bf16 v[116:119], v[148:151], v[232:235], v[116:119]
	v_mfma_f32_16x16x32_bf16 v[116:119], v[136:139], v[224:227], v[116:119]
	v_mfma_f32_16x16x32_bf16 v[88:91], v[178:181], v[204:207], v[88:91]
	v_mfma_f32_16x16x32_bf16 v[88:91], v[182:185], v[212:215], v[88:91]
	v_mfma_f32_16x16x32_bf16 v[100:103], v[200:203], v[212:215], v[100:103]
	v_mfma_f32_16x16x32_bf16 v[100:103], v[196:199], v[204:207], v[100:103]
	v_mfma_f32_16x16x32_bf16 v[104:107], v[196:199], v[208:211], v[104:107]
	v_mfma_f32_16x16x32_bf16 v[104:107], v[200:203], v[216:219], v[104:107]
	v_mfma_f32_16x16x32_bf16 v[96:99], v[182:185], v[216:219], v[96:99]
	v_mfma_f32_16x16x32_bf16 v[96:99], v[178:181], v[208:211], v[96:99]
	v_mfma_f32_16x16x32_bf16 v[112:115], v[178:181], v[220:223], v[112:115]
	v_mfma_f32_16x16x32_bf16 v[112:115], v[182:185], v[228:231], v[112:115]
	v_mfma_f32_16x16x32_bf16 v[124:127], v[200:203], v[228:231], v[124:127]
	v_mfma_f32_16x16x32_bf16 v[124:127], v[196:199], v[220:223], v[124:127]
	v_mfma_f32_16x16x32_bf16 v[128:131], v[196:199], v[224:227], v[128:131]
	v_mfma_f32_16x16x32_bf16 v[128:131], v[200:203], v[232:235], v[128:131]
	v_mfma_f32_16x16x32_bf16 v[120:123], v[182:185], v[232:235], v[120:123]
	v_mfma_f32_16x16x32_bf16 v[120:123], v[178:181], v[224:227], v[120:123]
	s_barrier
	v_add_u32_e32 v133, s82, v163
	v_add_u32_e32 v148, s82, v164
	ds_read_b128 v[136:139], v133
	ds_read_b128 v[148:151], v148
	v_add_u32_e32 v133, s80, v163
	v_add_u32_e32 v160, s80, v164
	ds_read_b128 v[152:155], v133
	ds_read_b128 v[174:177], v160
	v_add_u32_e32 v133, s83, v163
	v_add_u32_e32 v160, s83, v164
	ds_read_b128 v[178:181], v133
	ds_read_b128 v[182:185], v160
	v_add_u32_e32 v133, s81, v163
	v_add_u32_e32 v160, s81, v164
	ds_read_b128 v[196:199], v133
	ds_read_b128 v[200:203], v160
	s_mov_b32 m0, s5
	v_lshl_add_u64 v[160:161], s[70:71], 0, v[0:1]
	s_mov_b64 s[70:71], 0x20000
	ds_read_b128 v[204:207], v166 offset:32768
	ds_read_b128 v[208:211], v166 offset:34816
	ds_read_b128 v[212:215], v167 offset:32768
	ds_read_b128 v[216:219], v167 offset:34816
	ds_read_b128 v[220:223], v166 offset:36864
	ds_read_b128 v[224:227], v166 offset:38912
	ds_read_b128 v[228:231], v167 offset:36864
	ds_read_b128 v[232:235], v167 offset:38912
	global_load_lds_dwordx4 v[160:161], off
	v_lshl_add_u64 v[170:171], v[160:161], 0, s[70:71]
	s_mov_b32 m0, s17
	s_nop 0
	global_load_lds_dwordx4 v[170:171], off
	v_lshl_add_u64 v[170:171], v[160:161], 0, s[18:19]
	s_mov_b32 m0, s35
	v_lshl_add_u64 v[160:161], v[160:161], 0, s[22:23]
	global_load_lds_dwordx4 v[170:171], off
	s_mov_b32 m0, s38
	s_nop 0
	global_load_lds_dwordx4 v[160:161], off
	s_waitcnt vmcnt(8)
	s_waitcnt lgkmcnt(0)
	s_barrier
	v_mfma_f32_16x16x32_bf16 v[8:11], v[136:139], v[204:207], v[8:11]
	v_mfma_f32_16x16x32_bf16 v[8:11], v[148:151], v[212:215], v[8:11]
	v_mfma_f32_16x16x32_bf16 v[4:7], v[174:177], v[212:215], v[4:7]
	v_mfma_f32_16x16x32_bf16 v[4:7], v[152:155], v[204:207], v[4:7]
	v_mfma_f32_16x16x32_bf16 v[16:19], v[152:155], v[208:211], v[16:19]
	v_mfma_f32_16x16x32_bf16 v[16:19], v[174:177], v[216:219], v[16:19]
	v_mfma_f32_16x16x32_bf16 v[12:15], v[148:151], v[216:219], v[12:15]
	v_mfma_f32_16x16x32_bf16 v[12:15], v[136:139], v[208:211], v[12:15]
	v_mfma_f32_16x16x32_bf16 v[44:47], v[136:139], v[220:223], v[44:47]
	v_mfma_f32_16x16x32_bf16 v[44:47], v[148:151], v[228:231], v[44:47]
	v_mfma_f32_16x16x32_bf16 v[36:39], v[174:177], v[228:231], v[36:39]
	v_mfma_f32_16x16x32_bf16 v[36:39], v[152:155], v[220:223], v[36:39]
	v_mfma_f32_16x16x32_bf16 v[24:27], v[152:155], v[224:227], v[24:27]
	v_mfma_f32_16x16x32_bf16 v[24:27], v[174:177], v[232:235], v[24:27]
	v_mfma_f32_16x16x32_bf16 v[20:23], v[148:151], v[232:235], v[20:23]
	v_mfma_f32_16x16x32_bf16 v[20:23], v[136:139], v[224:227], v[20:23]
	v_mfma_f32_16x16x32_bf16 v[32:35], v[178:181], v[204:207], v[32:35]
	v_mfma_f32_16x16x32_bf16 v[32:35], v[182:185], v[212:215], v[32:35]
	v_mfma_f32_16x16x32_bf16 v[28:31], v[200:203], v[212:215], v[28:31]
	v_mfma_f32_16x16x32_bf16 v[28:31], v[196:199], v[204:207], v[28:31]
	v_mfma_f32_16x16x32_bf16 v[52:55], v[196:199], v[208:211], v[52:55]
	v_mfma_f32_16x16x32_bf16 v[52:55], v[200:203], v[216:219], v[52:55]
	v_mfma_f32_16x16x32_bf16 v[40:43], v[182:185], v[216:219], v[40:43]
	v_mfma_f32_16x16x32_bf16 v[40:43], v[178:181], v[208:211], v[40:43]
	v_mfma_f32_16x16x32_bf16 v[48:51], v[178:181], v[220:223], v[48:51]
	v_mfma_f32_16x16x32_bf16 v[48:51], v[182:185], v[228:231], v[48:51]
	v_mfma_f32_16x16x32_bf16 v[60:63], v[200:203], v[228:231], v[60:63]
	v_mfma_f32_16x16x32_bf16 v[60:63], v[196:199], v[220:223], v[60:63]
	v_mfma_f32_16x16x32_bf16 v[64:67], v[196:199], v[224:227], v[64:67]
	v_mfma_f32_16x16x32_bf16 v[64:67], v[200:203], v[232:235], v[64:67]
	v_mfma_f32_16x16x32_bf16 v[56:59], v[182:185], v[232:235], v[56:59]
	v_mfma_f32_16x16x32_bf16 v[56:59], v[178:181], v[224:227], v[56:59]
	s_barrier
	s_add_i32 s70, s82, s34
	v_lshl_add_u64 v[160:161], v[140:141], 0, s[36:37]
	s_mov_b32 m0, s70
	ds_read_b128 v[204:207], v166 offset:49152
	ds_read_b128 v[208:211], v166 offset:51200
	ds_read_b128 v[212:215], v167 offset:49152
	ds_read_b128 v[216:219], v167 offset:51200
	ds_read_b128 v[220:223], v166 offset:53248
	ds_read_b128 v[224:227], v166 offset:55296
	ds_read_b128 v[228:231], v167 offset:53248
	ds_read_b128 v[232:235], v167 offset:55296
	global_load_lds_dwordx4 v[160:161], off
	v_lshl_add_u64 v[160:161], v[140:141], 0, s[44:45]
	s_add_i32 m0, s70, 0x2000
	s_add_i32 s70, s83, s34
	global_load_lds_dwordx4 v[160:161], off
	v_lshl_add_u64 v[160:161], v[140:141], 0, s[46:47]
	s_mov_b32 m0, s70
	v_lshl_add_u64 v[140:141], v[140:141], 0, s[50:51]
	global_load_lds_dwordx4 v[160:161], off
	s_add_i32 m0, s70, 0x2000
	s_nop 0
	global_load_lds_dwordx4 v[140:141], off
	s_waitcnt vmcnt(4)
	s_waitcnt lgkmcnt(0)
	s_barrier
	v_mfma_f32_16x16x32_bf16 v[68:71], v[136:139], v[204:207], v[68:71]
	v_mfma_f32_16x16x32_bf16 v[68:71], v[148:151], v[212:215], v[68:71]
	v_mfma_f32_16x16x32_bf16 v[72:75], v[174:177], v[212:215], v[72:75]
	v_mfma_f32_16x16x32_bf16 v[72:75], v[152:155], v[204:207], v[72:75]
	v_mfma_f32_16x16x32_bf16 v[84:87], v[152:155], v[208:211], v[84:87]
	v_mfma_f32_16x16x32_bf16 v[84:87], v[174:177], v[216:219], v[84:87]
	v_mfma_f32_16x16x32_bf16 v[92:95], v[148:151], v[216:219], v[92:95]
	v_mfma_f32_16x16x32_bf16 v[92:95], v[136:139], v[208:211], v[92:95]
	v_mfma_f32_16x16x32_bf16 v[76:79], v[136:139], v[220:223], v[76:79]
	v_mfma_f32_16x16x32_bf16 v[76:79], v[148:151], v[228:231], v[76:79]
	v_mfma_f32_16x16x32_bf16 v[80:83], v[174:177], v[228:231], v[80:83]
	v_mfma_f32_16x16x32_bf16 v[80:83], v[152:155], v[220:223], v[80:83]
	v_mfma_f32_16x16x32_bf16 v[108:111], v[152:155], v[224:227], v[108:111]
	v_mfma_f32_16x16x32_bf16 v[108:111], v[174:177], v[232:235], v[108:111]
	v_mfma_f32_16x16x32_bf16 v[116:119], v[148:151], v[232:235], v[116:119]
	v_mfma_f32_16x16x32_bf16 v[116:119], v[136:139], v[224:227], v[116:119]
	v_mfma_f32_16x16x32_bf16 v[88:91], v[178:181], v[204:207], v[88:91]
	v_mfma_f32_16x16x32_bf16 v[88:91], v[182:185], v[212:215], v[88:91]
	v_mfma_f32_16x16x32_bf16 v[100:103], v[200:203], v[212:215], v[100:103]
	v_mfma_f32_16x16x32_bf16 v[100:103], v[196:199], v[204:207], v[100:103]
	v_mfma_f32_16x16x32_bf16 v[104:107], v[196:199], v[208:211], v[104:107]
	v_mfma_f32_16x16x32_bf16 v[104:107], v[200:203], v[216:219], v[104:107]
	v_mfma_f32_16x16x32_bf16 v[96:99], v[182:185], v[216:219], v[96:99]
	v_mfma_f32_16x16x32_bf16 v[96:99], v[178:181], v[208:211], v[96:99]
	v_mfma_f32_16x16x32_bf16 v[112:115], v[178:181], v[220:223], v[112:115]
	v_mfma_f32_16x16x32_bf16 v[112:115], v[182:185], v[228:231], v[112:115]
	v_mfma_f32_16x16x32_bf16 v[124:127], v[200:203], v[228:231], v[124:127]
	v_mfma_f32_16x16x32_bf16 v[124:127], v[196:199], v[220:223], v[124:127]
	v_mfma_f32_16x16x32_bf16 v[128:131], v[196:199], v[224:227], v[128:131]
	v_mfma_f32_16x16x32_bf16 v[128:131], v[200:203], v[232:235], v[128:131]
	v_mfma_f32_16x16x32_bf16 v[120:123], v[182:185], v[232:235], v[120:123]
	v_mfma_f32_16x16x32_bf16 v[120:123], v[178:181], v[224:227], v[120:123]
	s_barrier
	s_add_i32 s89, s89, 2
	s_add_u32 s26, s26, 0x100
	s_addc_u32 s27, s27, 0
	s_cmp_gt_u32 s89, 13
	s_cbranch_scc0 .LBB0_973
	s_and_b64 vcc, exec, s[52:53]
	s_cbranch_vccz .LBB0_976
	s_barrier

.LBB0_1134:
	s_ashr_i32 s57, s56, 31
	s_lshl_b64 s[60:61], s[56:57], 19
	s_add_u32 s60, s42, s60
	s_addc_u32 s61, s43, s61
	s_and_b64 s[62:63], s[10:11], exec
	s_cselect_b32 s57, s61, s27
	s_cselect_b32 s79, s60, s26
	s_ashr_i32 s59, s58, 31
	s_lshl_b64 s[62:63], s[58:59], 19
	v_readlane_b32 s70, v254, 7
	v_readlane_b32 s71, v254, 8
	s_add_u32 s62, s70, s62
	s_addc_u32 s63, s71, s63
	s_and_b64 s[70:71], s[10:11], exec
	s_cselect_b32 s59, s63, s69
	s_cselect_b32 s80, s62, s68
	s_add_u32 s81, s68, 0x100
	v_lshl_add_u64 v[138:139], s[26:27], 0, v[132:133]
	s_addc_u32 s82, s69, 0
	s_mov_b32 s83, -2
	s_mov_b64 s[68:69], 0
	ds_read_b128 v[168:171], v145
	ds_read_b128 v[174:177], v146
	ds_read_b128 v[178:181], v147
	ds_read_b128 v[182:185], v148
	ds_read_b128 v[194:197], v149
	ds_read_b128 v[198:201], v150
	ds_read_b128 v[202:205], v151
	ds_read_b128 v[206:209], v152
	s_add_u32 s70, s26, s68
	s_addc_u32 s71, s27, s69
	s_add_u32 s70, s70, 0x100
	s_addc_u32 s71, s71, 0
	s_add_u32 s84, s81, s68
	s_addc_u32 s85, s82, s69
	s_cmpk_eq_i32 s68, 0x700
	s_cselect_b32 s85, s59, s85
	s_cselect_b32 s84, s80, s84
	s_cselect_b32 s71, s57, s71
	s_cselect_b32 s70, s79, s70
	v_lshl_add_u64 v[140:141], v[138:139], 0, s[68:69]
	v_lshl_add_u64 v[242:243], v[140:141], 0, s[22:23]
	s_add_i32 m0, s34, 0x8000
	s_mov_b64 s[86:87], 0x20080
	ds_read_b128 v[210:213], v153
	ds_read_b128 v[214:217], v153 offset:2048
	ds_read_b128 v[218:221], v154
	ds_read_b128 v[222:225], v154 offset:2048
	ds_read_b128 v[226:229], v153 offset:4096
	ds_read_b128 v[230:233], v153 offset:6144
	ds_read_b128 v[234:237], v154 offset:4096
	ds_read_b128 v[238:241], v154 offset:6144
	global_load_lds_dwordx4 v[242:243], off
	v_lshl_add_u64 v[242:243], v[140:141], 0, s[86:87]
	s_add_i32 m0, s34, 0xa000
	s_mov_b64 s[86:87], 0x60080
	global_load_lds_dwordx4 v[242:243], off
	v_lshl_add_u64 v[242:243], v[140:141], 0, s[24:25]
	s_add_i32 m0, s34, 0xc000
	v_lshl_add_u64 v[140:141], v[140:141], 0, s[86:87]
	global_load_lds_dwordx4 v[242:243], off
	s_add_i32 m0, s34, 0xe000
	s_nop 0
	global_load_lds_dwordx4 v[140:141], off
	s_waitcnt lgkmcnt(0)
	s_barrier
	v_mfma_f32_16x16x32_bf16 v[128:131], v[168:171], v[210:213], 0
	v_mfma_f32_16x16x32_bf16 v[128:131], v[174:177], v[218:221], v[128:131]
	v_mfma_f32_16x16x32_bf16 v[124:127], v[178:181], v[210:213], 0
	v_mfma_f32_16x16x32_bf16 v[124:127], v[182:185], v[218:221], v[124:127]
	v_mfma_f32_16x16x32_bf16 v[108:111], v[178:181], v[214:217], 0
	v_mfma_f32_16x16x32_bf16 v[108:111], v[182:185], v[222:225], v[108:111]
	v_mfma_f32_16x16x32_bf16 v[112:115], v[168:171], v[214:217], 0
	v_mfma_f32_16x16x32_bf16 v[112:115], v[174:177], v[222:225], v[112:115]
	v_mfma_f32_16x16x32_bf16 v[96:99], v[168:171], v[226:229], 0
	v_mfma_f32_16x16x32_bf16 v[96:99], v[174:177], v[234:237], v[96:99]
	v_mfma_f32_16x16x32_bf16 v[92:95], v[178:181], v[226:229], 0
	v_mfma_f32_16x16x32_bf16 v[92:95], v[182:185], v[234:237], v[92:95]
	v_mfma_f32_16x16x32_bf16 v[76:79], v[178:181], v[230:233], 0
	v_mfma_f32_16x16x32_bf16 v[76:79], v[182:185], v[238:241], v[76:79]
	v_mfma_f32_16x16x32_bf16 v[80:83], v[168:171], v[230:233], 0
	v_mfma_f32_16x16x32_bf16 v[80:83], v[174:177], v[238:241], v[80:83]
	v_mfma_f32_16x16x32_bf16 v[120:123], v[194:197], v[210:213], 0
	v_mfma_f32_16x16x32_bf16 v[120:123], v[198:201], v[218:221], v[120:123]
	v_mfma_f32_16x16x32_bf16 v[116:119], v[202:205], v[210:213], 0
	v_mfma_f32_16x16x32_bf16 v[116:119], v[206:209], v[218:221], v[116:119]
	v_mfma_f32_16x16x32_bf16 v[100:103], v[202:205], v[214:217], 0
	v_mfma_f32_16x16x32_bf16 v[100:103], v[206:209], v[222:225], v[100:103]
	v_mfma_f32_16x16x32_bf16 v[104:107], v[194:197], v[214:217], 0
	v_mfma_f32_16x16x32_bf16 v[104:107], v[198:201], v[222:225], v[104:107]
	v_mfma_f32_16x16x32_bf16 v[88:91], v[194:197], v[226:229], 0
	v_mfma_f32_16x16x32_bf16 v[88:91], v[198:201], v[234:237], v[88:91]
	v_mfma_f32_16x16x32_bf16 v[84:87], v[202:205], v[226:229], 0
	v_mfma_f32_16x16x32_bf16 v[84:87], v[206:209], v[234:237], v[84:87]
	v_mfma_f32_16x16x32_bf16 v[68:71], v[202:205], v[230:233], 0
	v_mfma_f32_16x16x32_bf16 v[68:71], v[206:209], v[238:241], v[68:71]
	v_mfma_f32_16x16x32_bf16 v[72:75], v[194:197], v[230:233], 0
	v_mfma_f32_16x16x32_bf16 v[72:75], v[198:201], v[238:241], v[72:75]
	s_barrier
	v_lshl_add_u64 v[140:141], s[84:85], 0, v[158:159]
	s_add_i32 s84, s67, s3
	s_mov_b32 m0, s84
	ds_read_b128 v[210:213], v153 offset:16384
	ds_read_b128 v[214:217], v153 offset:18432
	ds_read_b128 v[218:221], v154 offset:16384
	ds_read_b128 v[222:225], v154 offset:18432
	ds_read_b128 v[226:229], v153 offset:20480
	ds_read_b128 v[230:233], v153 offset:22528
	ds_read_b128 v[234:237], v154 offset:20480
	ds_read_b128 v[238:241], v154 offset:22528
	global_load_lds_dwordx4 v[140:141], off
	v_lshl_add_u64 v[242:243], v[140:141], 0, s[0:1]
	s_add_i32 m0, s84, 0x2000
	s_add_i32 s84, s72, s3
	global_load_lds_dwordx4 v[242:243], off
	v_lshl_add_u64 v[242:243], v[140:141], 0, s[12:13]
	s_mov_b32 m0, s84
	s_nop 0
	global_load_lds_dwordx4 v[242:243], off
	v_lshl_add_u64 v[242:243], v[140:141], 0, s[14:15]
	s_add_i32 m0, s84, 0x2000
	s_nop 0
	global_load_lds_dwordx4 v[242:243], off
	s_waitcnt vmcnt(4)
	s_waitcnt lgkmcnt(0)
	s_barrier
	v_mfma_f32_16x16x32_bf16 v[64:67], v[168:171], v[210:213], 0
	v_mfma_f32_16x16x32_bf16 v[64:67], v[174:177], v[218:221], v[64:67]
	v_mfma_f32_16x16x32_bf16 v[60:63], v[178:181], v[210:213], 0
	v_mfma_f32_16x16x32_bf16 v[60:63], v[182:185], v[218:221], v[60:63]
	v_mfma_f32_16x16x32_bf16 v[44:47], v[178:181], v[214:217], 0
	v_mfma_f32_16x16x32_bf16 v[44:47], v[182:185], v[222:225], v[44:47]
	v_mfma_f32_16x16x32_bf16 v[48:51], v[168:171], v[214:217], 0
	v_mfma_f32_16x16x32_bf16 v[48:51], v[174:177], v[222:225], v[48:51]
	v_mfma_f32_16x16x32_bf16 v[32:35], v[168:171], v[226:229], 0
	v_mfma_f32_16x16x32_bf16 v[32:35], v[174:177], v[234:237], v[32:35]
	v_mfma_f32_16x16x32_bf16 v[28:31], v[178:181], v[226:229], 0
	v_mfma_f32_16x16x32_bf16 v[28:31], v[182:185], v[234:237], v[28:31]
	v_mfma_f32_16x16x32_bf16 v[12:15], v[178:181], v[230:233], 0
	v_mfma_f32_16x16x32_bf16 v[12:15], v[182:185], v[238:241], v[12:15]
	v_mfma_f32_16x16x32_bf16 v[16:19], v[168:171], v[230:233], 0
	v_mfma_f32_16x16x32_bf16 v[16:19], v[174:177], v[238:241], v[16:19]
	v_mfma_f32_16x16x32_bf16 v[56:59], v[194:197], v[210:213], 0
	v_mfma_f32_16x16x32_bf16 v[56:59], v[198:201], v[218:221], v[56:59]
	v_mfma_f32_16x16x32_bf16 v[52:55], v[202:205], v[210:213], 0
	v_mfma_f32_16x16x32_bf16 v[52:55], v[206:209], v[218:221], v[52:55]
	v_mfma_f32_16x16x32_bf16 v[36:39], v[202:205], v[214:217], 0
	v_mfma_f32_16x16x32_bf16 v[36:39], v[206:209], v[222:225], v[36:39]
	v_mfma_f32_16x16x32_bf16 v[40:43], v[194:197], v[214:217], 0
	v_mfma_f32_16x16x32_bf16 v[40:43], v[198:201], v[222:225], v[40:43]
	v_mfma_f32_16x16x32_bf16 v[24:27], v[194:197], v[226:229], 0
	v_mfma_f32_16x16x32_bf16 v[24:27], v[198:201], v[234:237], v[24:27]
	v_mfma_f32_16x16x32_bf16 v[20:23], v[202:205], v[226:229], 0
	v_mfma_f32_16x16x32_bf16 v[20:23], v[206:209], v[234:237], v[20:23]
	v_mfma_f32_16x16x32_bf16 v[4:7], v[202:205], v[230:233], 0
	v_mfma_f32_16x16x32_bf16 v[4:7], v[206:209], v[238:241], v[4:7]
	v_mfma_f32_16x16x32_bf16 v[8:11], v[194:197], v[230:233], 0
	v_mfma_f32_16x16x32_bf16 v[8:11], v[198:201], v[238:241], v[8:11]
	s_barrier
	ds_read_b128 v[168:171], v163
	ds_read_b128 v[174:177], v164
	ds_read_b128 v[178:181], v155
	ds_read_b128 v[182:185], v160
	ds_read_b128 v[194:197], v165
	ds_read_b128 v[198:201], v166
	ds_read_b128 v[202:205], v161
	ds_read_b128 v[206:209], v162
	s_mov_b32 m0, s34
	v_lshl_add_u64 v[242:243], s[70:71], 0, v[0:1]
	ds_read_b128 v[210:213], v153 offset:32768
	ds_read_b128 v[214:217], v153 offset:34816
	ds_read_b128 v[218:221], v154 offset:32768
	ds_read_b128 v[222:225], v154 offset:34816
	ds_read_b128 v[226:229], v153 offset:36864
	ds_read_b128 v[230:233], v153 offset:38912
	ds_read_b128 v[234:237], v154 offset:36864
	ds_read_b128 v[238:241], v154 offset:38912
	global_load_lds_dwordx4 v[242:243], off
	v_lshl_add_u64 v[244:245], v[242:243], 0, s[16:17]
	s_mov_b32 m0, s35
	s_nop 0
	global_load_lds_dwordx4 v[244:245], off
	v_lshl_add_u64 v[244:245], v[242:243], 0, s[0:1]
	s_mov_b32 m0, s38
	v_lshl_add_u64 v[242:243], v[242:243], 0, s[18:19]
	global_load_lds_dwordx4 v[244:245], off
	s_mov_b32 m0, s39
	s_nop 0
	global_load_lds_dwordx4 v[242:243], off
	s_waitcnt vmcnt(8)
	s_waitcnt lgkmcnt(0)
	s_barrier
	v_mfma_f32_16x16x32_bf16 v[128:131], v[168:171], v[210:213], v[128:131]
	v_mfma_f32_16x16x32_bf16 v[128:131], v[174:177], v[218:221], v[128:131]
	v_mfma_f32_16x16x32_bf16 v[124:127], v[182:185], v[218:221], v[124:127]
	v_mfma_f32_16x16x32_bf16 v[124:127], v[178:181], v[210:213], v[124:127]
	v_mfma_f32_16x16x32_bf16 v[108:111], v[178:181], v[214:217], v[108:111]
	v_mfma_f32_16x16x32_bf16 v[108:111], v[182:185], v[222:225], v[108:111]
	v_mfma_f32_16x16x32_bf16 v[112:115], v[174:177], v[222:225], v[112:115]
	v_mfma_f32_16x16x32_bf16 v[112:115], v[168:171], v[214:217], v[112:115]
	v_mfma_f32_16x16x32_bf16 v[96:99], v[168:171], v[226:229], v[96:99]
	v_mfma_f32_16x16x32_bf16 v[96:99], v[174:177], v[234:237], v[96:99]
	v_mfma_f32_16x16x32_bf16 v[92:95], v[182:185], v[234:237], v[92:95]
	v_mfma_f32_16x16x32_bf16 v[92:95], v[178:181], v[226:229], v[92:95]
	v_mfma_f32_16x16x32_bf16 v[76:79], v[178:181], v[230:233], v[76:79]
	v_mfma_f32_16x16x32_bf16 v[76:79], v[182:185], v[238:241], v[76:79]
	v_mfma_f32_16x16x32_bf16 v[80:83], v[174:177], v[238:241], v[80:83]
	v_mfma_f32_16x16x32_bf16 v[80:83], v[168:171], v[230:233], v[80:83]
	v_mfma_f32_16x16x32_bf16 v[120:123], v[194:197], v[210:213], v[120:123]
	v_mfma_f32_16x16x32_bf16 v[120:123], v[198:201], v[218:221], v[120:123]
	v_mfma_f32_16x16x32_bf16 v[116:119], v[206:209], v[218:221], v[116:119]
	v_mfma_f32_16x16x32_bf16 v[116:119], v[202:205], v[210:213], v[116:119]
	v_mfma_f32_16x16x32_bf16 v[100:103], v[202:205], v[214:217], v[100:103]
	v_mfma_f32_16x16x32_bf16 v[100:103], v[206:209], v[222:225], v[100:103]
	v_mfma_f32_16x16x32_bf16 v[104:107], v[198:201], v[222:225], v[104:107]
	v_mfma_f32_16x16x32_bf16 v[104:107], v[194:197], v[214:217], v[104:107]
	v_mfma_f32_16x16x32_bf16 v[88:91], v[194:197], v[226:229], v[88:91]
	v_mfma_f32_16x16x32_bf16 v[88:91], v[198:201], v[234:237], v[88:91]
	v_mfma_f32_16x16x32_bf16 v[84:87], v[206:209], v[234:237], v[84:87]
	v_mfma_f32_16x16x32_bf16 v[84:87], v[202:205], v[226:229], v[84:87]
	v_mfma_f32_16x16x32_bf16 v[68:71], v[202:205], v[230:233], v[68:71]
	v_mfma_f32_16x16x32_bf16 v[68:71], v[206:209], v[238:241], v[68:71]
	v_mfma_f32_16x16x32_bf16 v[72:75], v[198:201], v[238:241], v[72:75]
	v_mfma_f32_16x16x32_bf16 v[72:75], v[194:197], v[230:233], v[72:75]
	s_barrier
	s_add_i32 s70, s73, s3
	v_lshl_add_u64 v[242:243], v[140:141], 0, s[22:23]
	s_mov_b32 m0, s70
	ds_read_b128 v[210:213], v153 offset:49152
	ds_read_b128 v[214:217], v153 offset:51200
	ds_read_b128 v[218:221], v154 offset:49152
	ds_read_b128 v[222:225], v154 offset:51200
	ds_read_b128 v[226:229], v153 offset:53248
	ds_read_b128 v[230:233], v153 offset:55296
	ds_read_b128 v[234:237], v154 offset:53248
	ds_read_b128 v[238:241], v154 offset:55296
	global_load_lds_dwordx4 v[242:243], off
	v_lshl_add_u64 v[242:243], v[140:141], 0, s[24:25]
	s_add_i32 m0, s70, 0x2000
	s_add_i32 s70, s77, s3
	global_load_lds_dwordx4 v[242:243], off
	v_lshl_add_u64 v[242:243], v[140:141], 0, s[28:29]
	s_mov_b32 m0, s70
	v_lshl_add_u64 v[140:141], v[140:141], 0, s[36:37]
	global_load_lds_dwordx4 v[242:243], off
	s_add_i32 m0, s70, 0x2000
	s_nop 0
	global_load_lds_dwordx4 v[140:141], off
	s_waitcnt vmcnt(4)
	s_waitcnt lgkmcnt(0)
	s_barrier
	v_mfma_f32_16x16x32_bf16 v[64:67], v[168:171], v[210:213], v[64:67]
	v_mfma_f32_16x16x32_bf16 v[64:67], v[174:177], v[218:221], v[64:67]
	v_mfma_f32_16x16x32_bf16 v[60:63], v[182:185], v[218:221], v[60:63]
	v_mfma_f32_16x16x32_bf16 v[60:63], v[178:181], v[210:213], v[60:63]
	v_mfma_f32_16x16x32_bf16 v[44:47], v[178:181], v[214:217], v[44:47]
	v_mfma_f32_16x16x32_bf16 v[44:47], v[182:185], v[222:225], v[44:47]
	v_mfma_f32_16x16x32_bf16 v[48:51], v[174:177], v[222:225], v[48:51]
	v_mfma_f32_16x16x32_bf16 v[48:51], v[168:171], v[214:217], v[48:51]
	v_mfma_f32_16x16x32_bf16 v[32:35], v[168:171], v[226:229], v[32:35]
	v_mfma_f32_16x16x32_bf16 v[32:35], v[174:177], v[234:237], v[32:35]
	v_mfma_f32_16x16x32_bf16 v[28:31], v[182:185], v[234:237], v[28:31]
	v_mfma_f32_16x16x32_bf16 v[28:31], v[178:181], v[226:229], v[28:31]
	v_mfma_f32_16x16x32_bf16 v[12:15], v[178:181], v[230:233], v[12:15]
	v_mfma_f32_16x16x32_bf16 v[12:15], v[182:185], v[238:241], v[12:15]
	v_mfma_f32_16x16x32_bf16 v[16:19], v[174:177], v[238:241], v[16:19]
	v_mfma_f32_16x16x32_bf16 v[16:19], v[168:171], v[230:233], v[16:19]
	v_mfma_f32_16x16x32_bf16 v[56:59], v[194:197], v[210:213], v[56:59]
	v_mfma_f32_16x16x32_bf16 v[56:59], v[198:201], v[218:221], v[56:59]
	v_mfma_f32_16x16x32_bf16 v[52:55], v[206:209], v[218:221], v[52:55]
	v_mfma_f32_16x16x32_bf16 v[52:55], v[202:205], v[210:213], v[52:55]
	v_mfma_f32_16x16x32_bf16 v[36:39], v[202:205], v[214:217], v[36:39]
	v_mfma_f32_16x16x32_bf16 v[36:39], v[206:209], v[222:225], v[36:39]
	v_mfma_f32_16x16x32_bf16 v[40:43], v[198:201], v[222:225], v[40:43]
	v_mfma_f32_16x16x32_bf16 v[40:43], v[194:197], v[214:217], v[40:43]
	v_mfma_f32_16x16x32_bf16 v[24:27], v[194:197], v[226:229], v[24:27]
	v_mfma_f32_16x16x32_bf16 v[24:27], v[198:201], v[234:237], v[24:27]
	v_mfma_f32_16x16x32_bf16 v[20:23], v[206:209], v[234:237], v[20:23]
	v_mfma_f32_16x16x32_bf16 v[20:23], v[202:205], v[226:229], v[20:23]
	v_mfma_f32_16x16x32_bf16 v[4:7], v[202:205], v[230:233], v[4:7]
	v_mfma_f32_16x16x32_bf16 v[4:7], v[206:209], v[238:241], v[4:7]
	v_mfma_f32_16x16x32_bf16 v[8:11], v[198:201], v[238:241], v[8:11]
	v_mfma_f32_16x16x32_bf16 v[8:11], v[194:197], v[230:233], v[8:11]
	s_barrier
	s_add_i32 s83, s83, 2
	s_add_u32 s68, s68, 0x100
	s_addc_u32 s69, s69, 0
	s_cmp_gt_u32 s83, 13
.LBB0_1135:
	ds_read_b128 v[168:171], v145
	ds_read_b128 v[174:177], v146
	ds_read_b128 v[178:181], v147
	ds_read_b128 v[182:185], v148
	ds_read_b128 v[194:197], v149
	ds_read_b128 v[198:201], v150
	ds_read_b128 v[202:205], v151
	ds_read_b128 v[206:209], v152
	s_add_u32 s70, s26, s68
	s_addc_u32 s71, s27, s69
	s_add_u32 s70, s70, 0x100
	s_addc_u32 s71, s71, 0
	s_add_u32 s84, s81, s68
	s_addc_u32 s85, s82, s69
	s_cmpk_eq_i32 s68, 0x700
	s_cselect_b32 s85, s59, s85
	s_cselect_b32 s84, s80, s84
	s_cselect_b32 s71, s57, s71
	s_cselect_b32 s70, s79, s70
	v_lshl_add_u64 v[140:141], v[138:139], 0, s[68:69]
	v_lshl_add_u64 v[242:243], v[140:141], 0, s[22:23]
	s_add_i32 m0, s34, 0x8000
	s_mov_b64 s[86:87], 0x20080
	ds_read_b128 v[210:213], v153
	ds_read_b128 v[214:217], v153 offset:2048
	ds_read_b128 v[218:221], v154
	ds_read_b128 v[222:225], v154 offset:2048
	ds_read_b128 v[226:229], v153 offset:4096
	ds_read_b128 v[230:233], v153 offset:6144
	ds_read_b128 v[234:237], v154 offset:4096
	ds_read_b128 v[238:241], v154 offset:6144
	global_load_lds_dwordx4 v[242:243], off
	v_lshl_add_u64 v[242:243], v[140:141], 0, s[86:87]
	s_add_i32 m0, s34, 0xa000
	s_mov_b64 s[86:87], 0x60080
	global_load_lds_dwordx4 v[242:243], off
	v_lshl_add_u64 v[242:243], v[140:141], 0, s[24:25]
	s_add_i32 m0, s34, 0xc000
	v_lshl_add_u64 v[140:141], v[140:141], 0, s[86:87]
	global_load_lds_dwordx4 v[242:243], off
	s_add_i32 m0, s34, 0xe000
	s_nop 0
	global_load_lds_dwordx4 v[140:141], off
	s_waitcnt vmcnt(8)
	s_waitcnt lgkmcnt(0)
	s_barrier
	v_mfma_f32_16x16x32_bf16 v[128:131], v[168:171], v[210:213], v[128:131]
	v_mfma_f32_16x16x32_bf16 v[128:131], v[174:177], v[218:221], v[128:131]
	v_mfma_f32_16x16x32_bf16 v[124:127], v[182:185], v[218:221], v[124:127]
	v_mfma_f32_16x16x32_bf16 v[124:127], v[178:181], v[210:213], v[124:127]
	v_mfma_f32_16x16x32_bf16 v[108:111], v[178:181], v[214:217], v[108:111]
	v_mfma_f32_16x16x32_bf16 v[108:111], v[182:185], v[222:225], v[108:111]
	v_mfma_f32_16x16x32_bf16 v[112:115], v[174:177], v[222:225], v[112:115]
	v_mfma_f32_16x16x32_bf16 v[112:115], v[168:171], v[214:217], v[112:115]
	v_mfma_f32_16x16x32_bf16 v[96:99], v[168:171], v[226:229], v[96:99]
	v_mfma_f32_16x16x32_bf16 v[96:99], v[174:177], v[234:237], v[96:99]
	v_mfma_f32_16x16x32_bf16 v[92:95], v[182:185], v[234:237], v[92:95]
	v_mfma_f32_16x16x32_bf16 v[92:95], v[178:181], v[226:229], v[92:95]
	v_mfma_f32_16x16x32_bf16 v[76:79], v[178:181], v[230:233], v[76:79]
	v_mfma_f32_16x16x32_bf16 v[76:79], v[182:185], v[238:241], v[76:79]
	v_mfma_f32_16x16x32_bf16 v[80:83], v[174:177], v[238:241], v[80:83]
	v_mfma_f32_16x16x32_bf16 v[80:83], v[168:171], v[230:233], v[80:83]
	v_mfma_f32_16x16x32_bf16 v[120:123], v[194:197], v[210:213], v[120:123]
	v_mfma_f32_16x16x32_bf16 v[120:123], v[198:201], v[218:221], v[120:123]
	v_mfma_f32_16x16x32_bf16 v[116:119], v[206:209], v[218:221], v[116:119]
	v_mfma_f32_16x16x32_bf16 v[116:119], v[202:205], v[210:213], v[116:119]
	v_mfma_f32_16x16x32_bf16 v[100:103], v[202:205], v[214:217], v[100:103]
	v_mfma_f32_16x16x32_bf16 v[100:103], v[206:209], v[222:225], v[100:103]
	v_mfma_f32_16x16x32_bf16 v[104:107], v[198:201], v[222:225], v[104:107]
	v_mfma_f32_16x16x32_bf16 v[104:107], v[194:197], v[214:217], v[104:107]
	v_mfma_f32_16x16x32_bf16 v[88:91], v[194:197], v[226:229], v[88:91]
	v_mfma_f32_16x16x32_bf16 v[88:91], v[198:201], v[234:237], v[88:91]
	v_mfma_f32_16x16x32_bf16 v[84:87], v[206:209], v[234:237], v[84:87]
	v_mfma_f32_16x16x32_bf16 v[84:87], v[202:205], v[226:229], v[84:87]
	v_mfma_f32_16x16x32_bf16 v[68:71], v[202:205], v[230:233], v[68:71]
	v_mfma_f32_16x16x32_bf16 v[68:71], v[206:209], v[238:241], v[68:71]
	v_mfma_f32_16x16x32_bf16 v[72:75], v[198:201], v[238:241], v[72:75]
	v_mfma_f32_16x16x32_bf16 v[72:75], v[194:197], v[230:233], v[72:75]
	s_barrier
	v_lshl_add_u64 v[140:141], s[84:85], 0, v[158:159]
	s_add_i32 s84, s67, s3
	s_mov_b32 m0, s84
	ds_read_b128 v[210:213], v153 offset:16384
	ds_read_b128 v[214:217], v153 offset:18432
	ds_read_b128 v[218:221], v154 offset:16384
	ds_read_b128 v[222:225], v154 offset:18432
	ds_read_b128 v[226:229], v153 offset:20480
	ds_read_b128 v[230:233], v153 offset:22528
	ds_read_b128 v[234:237], v154 offset:20480
	ds_read_b128 v[238:241], v154 offset:22528
	global_load_lds_dwordx4 v[140:141], off
	v_lshl_add_u64 v[242:243], v[140:141], 0, s[0:1]
	s_add_i32 m0, s84, 0x2000
	s_add_i32 s84, s72, s3
	global_load_lds_dwordx4 v[242:243], off
	v_lshl_add_u64 v[242:243], v[140:141], 0, s[12:13]
	s_mov_b32 m0, s84
	s_nop 0
	global_load_lds_dwordx4 v[242:243], off
	v_lshl_add_u64 v[242:243], v[140:141], 0, s[14:15]
	s_add_i32 m0, s84, 0x2000
	s_nop 0
	global_load_lds_dwordx4 v[242:243], off
	s_waitcnt vmcnt(4)
	s_waitcnt lgkmcnt(0)
	s_barrier
	v_mfma_f32_16x16x32_bf16 v[64:67], v[168:171], v[210:213], v[64:67]
	v_mfma_f32_16x16x32_bf16 v[64:67], v[174:177], v[218:221], v[64:67]
	v_mfma_f32_16x16x32_bf16 v[60:63], v[182:185], v[218:221], v[60:63]
	v_mfma_f32_16x16x32_bf16 v[60:63], v[178:181], v[210:213], v[60:63]
	v_mfma_f32_16x16x32_bf16 v[44:47], v[178:181], v[214:217], v[44:47]
	v_mfma_f32_16x16x32_bf16 v[44:47], v[182:185], v[222:225], v[44:47]
	v_mfma_f32_16x16x32_bf16 v[48:51], v[174:177], v[222:225], v[48:51]
	v_mfma_f32_16x16x32_bf16 v[48:51], v[168:171], v[214:217], v[48:51]
	v_mfma_f32_16x16x32_bf16 v[32:35], v[168:171], v[226:229], v[32:35]
	v_mfma_f32_16x16x32_bf16 v[32:35], v[174:177], v[234:237], v[32:35]
	v_mfma_f32_16x16x32_bf16 v[28:31], v[182:185], v[234:237], v[28:31]
	v_mfma_f32_16x16x32_bf16 v[28:31], v[178:181], v[226:229], v[28:31]
	v_mfma_f32_16x16x32_bf16 v[12:15], v[178:181], v[230:233], v[12:15]
	v_mfma_f32_16x16x32_bf16 v[12:15], v[182:185], v[238:241], v[12:15]
	v_mfma_f32_16x16x32_bf16 v[16:19], v[174:177], v[238:241], v[16:19]
	v_mfma_f32_16x16x32_bf16 v[16:19], v[168:171], v[230:233], v[16:19]
	v_mfma_f32_16x16x32_bf16 v[56:59], v[194:197], v[210:213], v[56:59]
	v_mfma_f32_16x16x32_bf16 v[56:59], v[198:201], v[218:221], v[56:59]
	v_mfma_f32_16x16x32_bf16 v[52:55], v[206:209], v[218:221], v[52:55]
	v_mfma_f32_16x16x32_bf16 v[52:55], v[202:205], v[210:213], v[52:55]
	v_mfma_f32_16x16x32_bf16 v[36:39], v[202:205], v[214:217], v[36:39]
	v_mfma_f32_16x16x32_bf16 v[36:39], v[206:209], v[222:225], v[36:39]
	v_mfma_f32_16x16x32_bf16 v[40:43], v[198:201], v[222:225], v[40:43]
	v_mfma_f32_16x16x32_bf16 v[40:43], v[194:197], v[214:217], v[40:43]
	v_mfma_f32_16x16x32_bf16 v[24:27], v[194:197], v[226:229], v[24:27]
	v_mfma_f32_16x16x32_bf16 v[24:27], v[198:201], v[234:237], v[24:27]
	v_mfma_f32_16x16x32_bf16 v[20:23], v[206:209], v[234:237], v[20:23]
	v_mfma_f32_16x16x32_bf16 v[20:23], v[202:205], v[226:229], v[20:23]
	v_mfma_f32_16x16x32_bf16 v[4:7], v[202:205], v[230:233], v[4:7]
	v_mfma_f32_16x16x32_bf16 v[4:7], v[206:209], v[238:241], v[4:7]
	v_mfma_f32_16x16x32_bf16 v[8:11], v[198:201], v[238:241], v[8:11]
	v_mfma_f32_16x16x32_bf16 v[8:11], v[194:197], v[230:233], v[8:11]
	s_barrier
	ds_read_b128 v[168:171], v163
	ds_read_b128 v[174:177], v164
	ds_read_b128 v[178:181], v155
	ds_read_b128 v[182:185], v160
	ds_read_b128 v[194:197], v165
	ds_read_b128 v[198:201], v166
	ds_read_b128 v[202:205], v161
	ds_read_b128 v[206:209], v162
	s_mov_b32 m0, s34
	v_lshl_add_u64 v[242:243], s[70:71], 0, v[0:1]
	ds_read_b128 v[210:213], v153 offset:32768
	ds_read_b128 v[214:217], v153 offset:34816
	ds_read_b128 v[218:221], v154 offset:32768
	ds_read_b128 v[222:225], v154 offset:34816
	ds_read_b128 v[226:229], v153 offset:36864
	ds_read_b128 v[230:233], v153 offset:38912
	ds_read_b128 v[234:237], v154 offset:36864
	ds_read_b128 v[238:241], v154 offset:38912
	global_load_lds_dwordx4 v[242:243], off
	v_lshl_add_u64 v[244:245], v[242:243], 0, s[16:17]
	s_mov_b32 m0, s35
	s_nop 0
	global_load_lds_dwordx4 v[244:245], off
	v_lshl_add_u64 v[244:245], v[242:243], 0, s[0:1]
	s_mov_b32 m0, s38
	v_lshl_add_u64 v[242:243], v[242:243], 0, s[18:19]
	global_load_lds_dwordx4 v[244:245], off
	s_mov_b32 m0, s39
	s_nop 0
	global_load_lds_dwordx4 v[242:243], off
	s_waitcnt vmcnt(8)
	s_waitcnt lgkmcnt(0)
	s_barrier
	v_mfma_f32_16x16x32_bf16 v[128:131], v[168:171], v[210:213], v[128:131]
	v_mfma_f32_16x16x32_bf16 v[128:131], v[174:177], v[218:221], v[128:131]
	v_mfma_f32_16x16x32_bf16 v[124:127], v[182:185], v[218:221], v[124:127]
	v_mfma_f32_16x16x32_bf16 v[124:127], v[178:181], v[210:213], v[124:127]
	v_mfma_f32_16x16x32_bf16 v[108:111], v[178:181], v[214:217], v[108:111]
	v_mfma_f32_16x16x32_bf16 v[108:111], v[182:185], v[222:225], v[108:111]
	v_mfma_f32_16x16x32_bf16 v[112:115], v[174:177], v[222:225], v[112:115]
	v_mfma_f32_16x16x32_bf16 v[112:115], v[168:171], v[214:217], v[112:115]
	v_mfma_f32_16x16x32_bf16 v[96:99], v[168:171], v[226:229], v[96:99]
	v_mfma_f32_16x16x32_bf16 v[96:99], v[174:177], v[234:237], v[96:99]
	v_mfma_f32_16x16x32_bf16 v[92:95], v[182:185], v[234:237], v[92:95]
	v_mfma_f32_16x16x32_bf16 v[92:95], v[178:181], v[226:229], v[92:95]
	v_mfma_f32_16x16x32_bf16 v[76:79], v[178:181], v[230:233], v[76:79]
	v_mfma_f32_16x16x32_bf16 v[76:79], v[182:185], v[238:241], v[76:79]
	v_mfma_f32_16x16x32_bf16 v[80:83], v[174:177], v[238:241], v[80:83]
	v_mfma_f32_16x16x32_bf16 v[80:83], v[168:171], v[230:233], v[80:83]
	v_mfma_f32_16x16x32_bf16 v[120:123], v[194:197], v[210:213], v[120:123]
	v_mfma_f32_16x16x32_bf16 v[120:123], v[198:201], v[218:221], v[120:123]
	v_mfma_f32_16x16x32_bf16 v[116:119], v[206:209], v[218:221], v[116:119]
	v_mfma_f32_16x16x32_bf16 v[116:119], v[202:205], v[210:213], v[116:119]
	v_mfma_f32_16x16x32_bf16 v[100:103], v[202:205], v[214:217], v[100:103]
	v_mfma_f32_16x16x32_bf16 v[100:103], v[206:209], v[222:225], v[100:103]
	v_mfma_f32_16x16x32_bf16 v[104:107], v[198:201], v[222:225], v[104:107]
	v_mfma_f32_16x16x32_bf16 v[104:107], v[194:197], v[214:217], v[104:107]
	v_mfma_f32_16x16x32_bf16 v[88:91], v[194:197], v[226:229], v[88:91]
	v_mfma_f32_16x16x32_bf16 v[88:91], v[198:201], v[234:237], v[88:91]
	v_mfma_f32_16x16x32_bf16 v[84:87], v[206:209], v[234:237], v[84:87]
	v_mfma_f32_16x16x32_bf16 v[84:87], v[202:205], v[226:229], v[84:87]
	v_mfma_f32_16x16x32_bf16 v[68:71], v[202:205], v[230:233], v[68:71]
	v_mfma_f32_16x16x32_bf16 v[68:71], v[206:209], v[238:241], v[68:71]
	v_mfma_f32_16x16x32_bf16 v[72:75], v[198:201], v[238:241], v[72:75]
	v_mfma_f32_16x16x32_bf16 v[72:75], v[194:197], v[230:233], v[72:75]
	s_barrier
	s_add_i32 s70, s73, s3
	v_lshl_add_u64 v[242:243], v[140:141], 0, s[22:23]
	s_mov_b32 m0, s70
	ds_read_b128 v[210:213], v153 offset:49152
	ds_read_b128 v[214:217], v153 offset:51200
	ds_read_b128 v[218:221], v154 offset:49152
	ds_read_b128 v[222:225], v154 offset:51200
	ds_read_b128 v[226:229], v153 offset:53248
	ds_read_b128 v[230:233], v153 offset:55296
	ds_read_b128 v[234:237], v154 offset:53248
	ds_read_b128 v[238:241], v154 offset:55296
	global_load_lds_dwordx4 v[242:243], off
	v_lshl_add_u64 v[242:243], v[140:141], 0, s[24:25]
	s_add_i32 m0, s70, 0x2000
	s_add_i32 s70, s77, s3
	global_load_lds_dwordx4 v[242:243], off
	v_lshl_add_u64 v[242:243], v[140:141], 0, s[28:29]
	s_mov_b32 m0, s70
	v_lshl_add_u64 v[140:141], v[140:141], 0, s[36:37]
	global_load_lds_dwordx4 v[242:243], off
	s_add_i32 m0, s70, 0x2000
	s_nop 0
	global_load_lds_dwordx4 v[140:141], off
	s_waitcnt vmcnt(4)
	s_waitcnt lgkmcnt(0)
	s_barrier
	v_mfma_f32_16x16x32_bf16 v[64:67], v[168:171], v[210:213], v[64:67]
	v_mfma_f32_16x16x32_bf16 v[64:67], v[174:177], v[218:221], v[64:67]
	v_mfma_f32_16x16x32_bf16 v[60:63], v[182:185], v[218:221], v[60:63]
	v_mfma_f32_16x16x32_bf16 v[60:63], v[178:181], v[210:213], v[60:63]
	v_mfma_f32_16x16x32_bf16 v[44:47], v[178:181], v[214:217], v[44:47]
	v_mfma_f32_16x16x32_bf16 v[44:47], v[182:185], v[222:225], v[44:47]
	v_mfma_f32_16x16x32_bf16 v[48:51], v[174:177], v[222:225], v[48:51]
	v_mfma_f32_16x16x32_bf16 v[48:51], v[168:171], v[214:217], v[48:51]
	v_mfma_f32_16x16x32_bf16 v[32:35], v[168:171], v[226:229], v[32:35]
	v_mfma_f32_16x16x32_bf16 v[32:35], v[174:177], v[234:237], v[32:35]
	v_mfma_f32_16x16x32_bf16 v[28:31], v[182:185], v[234:237], v[28:31]
	v_mfma_f32_16x16x32_bf16 v[28:31], v[178:181], v[226:229], v[28:31]
	v_mfma_f32_16x16x32_bf16 v[12:15], v[178:181], v[230:233], v[12:15]
	v_mfma_f32_16x16x32_bf16 v[12:15], v[182:185], v[238:241], v[12:15]
	v_mfma_f32_16x16x32_bf16 v[16:19], v[174:177], v[238:241], v[16:19]
	v_mfma_f32_16x16x32_bf16 v[16:19], v[168:171], v[230:233], v[16:19]
	v_mfma_f32_16x16x32_bf16 v[56:59], v[194:197], v[210:213], v[56:59]
	v_mfma_f32_16x16x32_bf16 v[56:59], v[198:201], v[218:221], v[56:59]
	v_mfma_f32_16x16x32_bf16 v[52:55], v[206:209], v[218:221], v[52:55]
	v_mfma_f32_16x16x32_bf16 v[52:55], v[202:205], v[210:213], v[52:55]
	v_mfma_f32_16x16x32_bf16 v[36:39], v[202:205], v[214:217], v[36:39]
	v_mfma_f32_16x16x32_bf16 v[36:39], v[206:209], v[222:225], v[36:39]
	v_mfma_f32_16x16x32_bf16 v[40:43], v[198:201], v[222:225], v[40:43]
	v_mfma_f32_16x16x32_bf16 v[40:43], v[194:197], v[214:217], v[40:43]
	v_mfma_f32_16x16x32_bf16 v[24:27], v[194:197], v[226:229], v[24:27]
	v_mfma_f32_16x16x32_bf16 v[24:27], v[198:201], v[234:237], v[24:27]
	v_mfma_f32_16x16x32_bf16 v[20:23], v[206:209], v[234:237], v[20:23]
	v_mfma_f32_16x16x32_bf16 v[20:23], v[202:205], v[226:229], v[20:23]
	v_mfma_f32_16x16x32_bf16 v[4:7], v[202:205], v[230:233], v[4:7]
	v_mfma_f32_16x16x32_bf16 v[4:7], v[206:209], v[238:241], v[4:7]
	v_mfma_f32_16x16x32_bf16 v[8:11], v[198:201], v[238:241], v[8:11]
	v_mfma_f32_16x16x32_bf16 v[8:11], v[194:197], v[230:233], v[8:11]
	s_barrier
	s_add_i32 s83, s83, 2
	s_add_u32 s68, s68, 0x100
	s_addc_u32 s69, s69, 0
	s_cmp_gt_u32 s83, 13
	s_cbranch_scc0 .LBB0_1135
	s_and_b64 vcc, exec, s[40:41]
	s_cbranch_vccz .LBB0_1138
	s_barrier

.LBB0_1371:
	v_add_u32_e32 v147, s64, v143
	v_add_u32_e32 v152, s64, v144
	ds_read_b128 v[148:151], v147
	ds_read_b128 v[152:155], v152
	v_add_u32_e32 v147, s65, v143
	v_add_u32_e32 v162, s65, v144
	s_add_u32 s58, s18, s56
	ds_read_b128 v[158:161], v147
	ds_read_b128 v[162:165], v162
	v_add_u32_e32 v147, s66, v143
	s_addc_u32 s59, s19, s57
	v_add_u32_e32 v166, s66, v144
	ds_read_b128 v[170:173], v147
	ds_read_b128 v[174:177], v166
	v_add_u32_e32 v147, s67, v143
	s_add_u32 s58, s58, 0x100
	v_add_u32_e32 v166, s67, v144
	ds_read_b128 v[178:181], v147
	ds_read_b128 v[182:185], v166
	s_addc_u32 s59, s59, 0
	s_add_u32 s78, s53, s56
	s_addc_u32 s79, s72, s57
	s_cmpk_eq_i32 s56, 0x1f00
	s_cselect_b32 s79, s49, s79
	s_cselect_b32 s78, s76, s78
	s_cselect_b32 s59, s51, s59
	s_cselect_b32 s58, s73, s58
	v_lshl_add_u64 v[166:167], v[140:141], 0, s[56:57]
	v_lshl_add_u64 v[218:219], v[166:167], 0, s[24:25]
	s_add_i32 m0, s35, 0x8000
	ds_read_b128 v[186:189], v145
	ds_read_b128 v[190:193], v145 offset:2048
	ds_read_b128 v[194:197], v146
	ds_read_b128 v[198:201], v146 offset:2048
	ds_read_b128 v[202:205], v145 offset:4096
	ds_read_b128 v[206:209], v145 offset:6144
	ds_read_b128 v[210:213], v146 offset:4096
	ds_read_b128 v[214:217], v146 offset:6144
	global_load_lds_dwordx4 v[218:219], off
	v_lshl_add_u64 v[218:219], v[166:167], 0, s[44:45]
	s_add_i32 m0, s35, 0xa000
	s_nop 0
	global_load_lds_dwordx4 v[218:219], off
	v_lshl_add_u64 v[218:219], v[166:167], 0, s[28:29]
	s_add_i32 m0, s35, 0xc000
	v_lshl_add_u64 v[166:167], v[166:167], 0, s[46:47]
	global_load_lds_dwordx4 v[218:219], off
	s_add_i32 m0, s35, 0xe000
	s_nop 0
	global_load_lds_dwordx4 v[166:167], off
	s_waitcnt vmcnt(8)
	s_waitcnt lgkmcnt(0)
	s_barrier
	v_mfma_f32_16x16x32_bf16 v[128:131], v[148:151], v[186:189], v[128:131]
	v_mfma_f32_16x16x32_bf16 v[128:131], v[152:155], v[194:197], v[128:131]
	v_mfma_f32_16x16x32_bf16 v[124:127], v[162:165], v[194:197], v[124:127]
	v_mfma_f32_16x16x32_bf16 v[124:127], v[158:161], v[186:189], v[124:127]
	v_mfma_f32_16x16x32_bf16 v[108:111], v[158:161], v[190:193], v[108:111]
	v_mfma_f32_16x16x32_bf16 v[108:111], v[162:165], v[198:201], v[108:111]
	v_mfma_f32_16x16x32_bf16 v[112:115], v[152:155], v[198:201], v[112:115]
	v_mfma_f32_16x16x32_bf16 v[112:115], v[148:151], v[190:193], v[112:115]
	v_mfma_f32_16x16x32_bf16 v[96:99], v[148:151], v[202:205], v[96:99]
	v_mfma_f32_16x16x32_bf16 v[96:99], v[152:155], v[210:213], v[96:99]
	v_mfma_f32_16x16x32_bf16 v[92:95], v[162:165], v[210:213], v[92:95]
	v_mfma_f32_16x16x32_bf16 v[92:95], v[158:161], v[202:205], v[92:95]
	v_mfma_f32_16x16x32_bf16 v[76:79], v[158:161], v[206:209], v[76:79]
	v_mfma_f32_16x16x32_bf16 v[76:79], v[162:165], v[214:217], v[76:79]
	v_mfma_f32_16x16x32_bf16 v[80:83], v[152:155], v[214:217], v[80:83]
	v_mfma_f32_16x16x32_bf16 v[80:83], v[148:151], v[206:209], v[80:83]
	v_mfma_f32_16x16x32_bf16 v[120:123], v[170:173], v[186:189], v[120:123]
	v_mfma_f32_16x16x32_bf16 v[120:123], v[174:177], v[194:197], v[120:123]
	v_mfma_f32_16x16x32_bf16 v[116:119], v[182:185], v[194:197], v[116:119]
	v_mfma_f32_16x16x32_bf16 v[116:119], v[178:181], v[186:189], v[116:119]
	v_mfma_f32_16x16x32_bf16 v[100:103], v[178:181], v[190:193], v[100:103]
	v_mfma_f32_16x16x32_bf16 v[100:103], v[182:185], v[198:201], v[100:103]
	v_mfma_f32_16x16x32_bf16 v[104:107], v[174:177], v[198:201], v[104:107]
	v_mfma_f32_16x16x32_bf16 v[104:107], v[170:173], v[190:193], v[104:107]
	v_mfma_f32_16x16x32_bf16 v[88:91], v[170:173], v[202:205], v[88:91]
	v_mfma_f32_16x16x32_bf16 v[88:91], v[174:177], v[210:213], v[88:91]
	v_mfma_f32_16x16x32_bf16 v[84:87], v[182:185], v[210:213], v[84:87]
	v_mfma_f32_16x16x32_bf16 v[84:87], v[178:181], v[202:205], v[84:87]
	v_mfma_f32_16x16x32_bf16 v[68:71], v[178:181], v[206:209], v[68:71]
	v_mfma_f32_16x16x32_bf16 v[68:71], v[182:185], v[214:217], v[68:71]
	v_mfma_f32_16x16x32_bf16 v[72:75], v[174:177], v[214:217], v[72:75]
	v_mfma_f32_16x16x32_bf16 v[72:75], v[170:173], v[206:209], v[72:75]
	s_barrier
	v_lshl_add_u64 v[166:167], s[78:79], 0, v[132:133]
	s_add_i32 s78, s64, s34
	s_mov_b32 m0, s78
	ds_read_b128 v[186:189], v145 offset:16384
	ds_read_b128 v[190:193], v145 offset:18432
	ds_read_b128 v[194:197], v146 offset:16384
	ds_read_b128 v[198:201], v146 offset:18432
	ds_read_b128 v[202:205], v145 offset:20480
	ds_read_b128 v[206:209], v145 offset:22528
	ds_read_b128 v[210:213], v146 offset:20480
	ds_read_b128 v[214:217], v146 offset:22528
	global_load_lds_dwordx4 v[166:167], off
	v_lshl_add_u64 v[218:219], v[166:167], 0, s[10:11]
	s_add_i32 m0, s78, 0x2000
	s_add_i32 s78, s66, s34
	global_load_lds_dwordx4 v[218:219], off
	v_lshl_add_u64 v[218:219], v[166:167], 0, s[14:15]
	s_mov_b32 m0, s78
	s_nop 0
	global_load_lds_dwordx4 v[218:219], off
	v_lshl_add_u64 v[218:219], v[166:167], 0, s[16:17]
	s_add_i32 m0, s78, 0x2000
	s_nop 0
	global_load_lds_dwordx4 v[218:219], off
	s_waitcnt vmcnt(4)
	s_waitcnt lgkmcnt(0)
	s_barrier
	v_mfma_f32_16x16x32_bf16 v[64:67], v[148:151], v[186:189], v[64:67]
	v_mfma_f32_16x16x32_bf16 v[64:67], v[152:155], v[194:197], v[64:67]
	v_mfma_f32_16x16x32_bf16 v[60:63], v[162:165], v[194:197], v[60:63]
	v_mfma_f32_16x16x32_bf16 v[60:63], v[158:161], v[186:189], v[60:63]
	v_mfma_f32_16x16x32_bf16 v[44:47], v[158:161], v[190:193], v[44:47]
	v_mfma_f32_16x16x32_bf16 v[44:47], v[162:165], v[198:201], v[44:47]
	v_mfma_f32_16x16x32_bf16 v[48:51], v[152:155], v[198:201], v[48:51]
	v_mfma_f32_16x16x32_bf16 v[48:51], v[148:151], v[190:193], v[48:51]
	v_mfma_f32_16x16x32_bf16 v[32:35], v[148:151], v[202:205], v[32:35]
	v_mfma_f32_16x16x32_bf16 v[32:35], v[152:155], v[210:213], v[32:35]
	v_mfma_f32_16x16x32_bf16 v[28:31], v[162:165], v[210:213], v[28:31]
	v_mfma_f32_16x16x32_bf16 v[28:31], v[158:161], v[202:205], v[28:31]
	v_mfma_f32_16x16x32_bf16 v[12:15], v[158:161], v[206:209], v[12:15]
	v_mfma_f32_16x16x32_bf16 v[12:15], v[162:165], v[214:217], v[12:15]
	v_mfma_f32_16x16x32_bf16 v[16:19], v[152:155], v[214:217], v[16:19]
	v_mfma_f32_16x16x32_bf16 v[16:19], v[148:151], v[206:209], v[16:19]
	v_mfma_f32_16x16x32_bf16 v[56:59], v[170:173], v[186:189], v[56:59]
	v_mfma_f32_16x16x32_bf16 v[56:59], v[174:177], v[194:197], v[56:59]
	v_mfma_f32_16x16x32_bf16 v[52:55], v[182:185], v[194:197], v[52:55]
	v_mfma_f32_16x16x32_bf16 v[52:55], v[178:181], v[186:189], v[52:55]
	v_mfma_f32_16x16x32_bf16 v[36:39], v[178:181], v[190:193], v[36:39]
	v_mfma_f32_16x16x32_bf16 v[36:39], v[182:185], v[198:201], v[36:39]
	v_mfma_f32_16x16x32_bf16 v[40:43], v[174:177], v[198:201], v[40:43]
	v_mfma_f32_16x16x32_bf16 v[40:43], v[170:173], v[190:193], v[40:43]
	v_mfma_f32_16x16x32_bf16 v[24:27], v[170:173], v[202:205], v[24:27]
	v_mfma_f32_16x16x32_bf16 v[24:27], v[174:177], v[210:213], v[24:27]
	v_mfma_f32_16x16x32_bf16 v[20:23], v[182:185], v[210:213], v[20:23]
	v_mfma_f32_16x16x32_bf16 v[20:23], v[178:181], v[202:205], v[20:23]
	v_mfma_f32_16x16x32_bf16 v[4:7], v[178:181], v[206:209], v[4:7]
	v_mfma_f32_16x16x32_bf16 v[4:7], v[182:185], v[214:217], v[4:7]
	v_mfma_f32_16x16x32_bf16 v[8:11], v[174:177], v[214:217], v[8:11]
	v_mfma_f32_16x16x32_bf16 v[8:11], v[170:173], v[206:209], v[8:11]
	s_barrier
	v_add_u32_e32 v147, s70, v143
	v_add_u32_e32 v152, s70, v144
	ds_read_b128 v[148:151], v147
	ds_read_b128 v[152:155], v152
	v_add_u32_e32 v147, s68, v143
	v_add_u32_e32 v162, s68, v144
	ds_read_b128 v[158:161], v147
	ds_read_b128 v[162:165], v162
	v_add_u32_e32 v147, s71, v143
	v_add_u32_e32 v169, s71, v144
	ds_read_b128 v[170:173], v147
	ds_read_b128 v[174:177], v169
	v_add_u32_e32 v147, s69, v143
	v_add_u32_e32 v169, s69, v144
	ds_read_b128 v[178:181], v147
	ds_read_b128 v[182:185], v169
	s_mov_b32 m0, s35
	v_lshl_add_u64 v[218:219], s[58:59], 0, v[0:1]
	ds_read_b128 v[186:189], v145 offset:32768
	ds_read_b128 v[190:193], v145 offset:34816
	ds_read_b128 v[194:197], v146 offset:32768
	ds_read_b128 v[198:201], v146 offset:34816
	ds_read_b128 v[202:205], v145 offset:36864
	ds_read_b128 v[206:209], v145 offset:38912
	ds_read_b128 v[210:213], v146 offset:36864
	ds_read_b128 v[214:217], v146 offset:38912
	global_load_lds_dwordx4 v[218:219], off
	v_lshl_add_u64 v[220:221], v[218:219], 0, s[20:21]
	s_mov_b32 m0, s39
	s_nop 0
	global_load_lds_dwordx4 v[220:221], off
	v_lshl_add_u64 v[220:221], v[218:219], 0, s[10:11]
	s_mov_b32 m0, s60
	v_lshl_add_u64 v[218:219], v[218:219], 0, s[22:23]
	global_load_lds_dwordx4 v[220:221], off
	s_mov_b32 m0, s61
	s_nop 0
	global_load_lds_dwordx4 v[218:219], off
	s_waitcnt vmcnt(8)
	s_waitcnt lgkmcnt(0)
	s_barrier
	v_mfma_f32_16x16x32_bf16 v[128:131], v[148:151], v[186:189], v[128:131]
	v_mfma_f32_16x16x32_bf16 v[128:131], v[152:155], v[194:197], v[128:131]
	v_mfma_f32_16x16x32_bf16 v[124:127], v[162:165], v[194:197], v[124:127]
	v_mfma_f32_16x16x32_bf16 v[124:127], v[158:161], v[186:189], v[124:127]
	v_mfma_f32_16x16x32_bf16 v[108:111], v[158:161], v[190:193], v[108:111]
	v_mfma_f32_16x16x32_bf16 v[108:111], v[162:165], v[198:201], v[108:111]
	v_mfma_f32_16x16x32_bf16 v[112:115], v[152:155], v[198:201], v[112:115]
	v_mfma_f32_16x16x32_bf16 v[112:115], v[148:151], v[190:193], v[112:115]
	v_mfma_f32_16x16x32_bf16 v[96:99], v[148:151], v[202:205], v[96:99]
	v_mfma_f32_16x16x32_bf16 v[96:99], v[152:155], v[210:213], v[96:99]
	v_mfma_f32_16x16x32_bf16 v[92:95], v[162:165], v[210:213], v[92:95]
	v_mfma_f32_16x16x32_bf16 v[92:95], v[158:161], v[202:205], v[92:95]
	v_mfma_f32_16x16x32_bf16 v[76:79], v[158:161], v[206:209], v[76:79]
	v_mfma_f32_16x16x32_bf16 v[76:79], v[162:165], v[214:217], v[76:79]
	v_mfma_f32_16x16x32_bf16 v[80:83], v[152:155], v[214:217], v[80:83]
	v_mfma_f32_16x16x32_bf16 v[80:83], v[148:151], v[206:209], v[80:83]
	v_mfma_f32_16x16x32_bf16 v[120:123], v[170:173], v[186:189], v[120:123]
	v_mfma_f32_16x16x32_bf16 v[120:123], v[174:177], v[194:197], v[120:123]
	v_mfma_f32_16x16x32_bf16 v[116:119], v[182:185], v[194:197], v[116:119]
	v_mfma_f32_16x16x32_bf16 v[116:119], v[178:181], v[186:189], v[116:119]
	v_mfma_f32_16x16x32_bf16 v[100:103], v[178:181], v[190:193], v[100:103]
	v_mfma_f32_16x16x32_bf16 v[100:103], v[182:185], v[198:201], v[100:103]
	v_mfma_f32_16x16x32_bf16 v[104:107], v[174:177], v[198:201], v[104:107]
	v_mfma_f32_16x16x32_bf16 v[104:107], v[170:173], v[190:193], v[104:107]
	v_mfma_f32_16x16x32_bf16 v[88:91], v[170:173], v[202:205], v[88:91]
	v_mfma_f32_16x16x32_bf16 v[88:91], v[174:177], v[210:213], v[88:91]
	v_mfma_f32_16x16x32_bf16 v[84:87], v[182:185], v[210:213], v[84:87]
	v_mfma_f32_16x16x32_bf16 v[84:87], v[178:181], v[202:205], v[84:87]
	v_mfma_f32_16x16x32_bf16 v[68:71], v[178:181], v[206:209], v[68:71]
	v_mfma_f32_16x16x32_bf16 v[68:71], v[182:185], v[214:217], v[68:71]
	v_mfma_f32_16x16x32_bf16 v[72:75], v[174:177], v[214:217], v[72:75]
	v_mfma_f32_16x16x32_bf16 v[72:75], v[170:173], v[206:209], v[72:75]
	s_barrier
	s_add_i32 s58, s70, s34
	v_lshl_add_u64 v[218:219], v[166:167], 0, s[24:25]
	s_mov_b32 m0, s58
	ds_read_b128 v[186:189], v145 offset:49152
	ds_read_b128 v[190:193], v145 offset:51200
	ds_read_b128 v[194:197], v146 offset:49152
	ds_read_b128 v[198:201], v146 offset:51200
	ds_read_b128 v[202:205], v145 offset:53248
	ds_read_b128 v[206:209], v145 offset:55296
	ds_read_b128 v[210:213], v146 offset:53248
	ds_read_b128 v[214:217], v146 offset:55296
	global_load_lds_dwordx4 v[218:219], off
	v_lshl_add_u64 v[218:219], v[166:167], 0, s[28:29]
	s_add_i32 m0, s58, 0x2000
	s_add_i32 s58, s71, s34
	global_load_lds_dwordx4 v[218:219], off
	v_lshl_add_u64 v[218:219], v[166:167], 0, s[36:37]
	s_mov_b32 m0, s58
	v_lshl_add_u64 v[166:167], v[166:167], 0, s[40:41]
	global_load_lds_dwordx4 v[218:219], off
	s_add_i32 m0, s58, 0x2000
	s_nop 0
	global_load_lds_dwordx4 v[166:167], off
	s_waitcnt vmcnt(4)
	s_waitcnt lgkmcnt(0)
	s_barrier
	v_mfma_f32_16x16x32_bf16 v[64:67], v[148:151], v[186:189], v[64:67]
	v_mfma_f32_16x16x32_bf16 v[64:67], v[152:155], v[194:197], v[64:67]
	v_mfma_f32_16x16x32_bf16 v[60:63], v[162:165], v[194:197], v[60:63]
	v_mfma_f32_16x16x32_bf16 v[60:63], v[158:161], v[186:189], v[60:63]
	v_mfma_f32_16x16x32_bf16 v[44:47], v[158:161], v[190:193], v[44:47]
	v_mfma_f32_16x16x32_bf16 v[44:47], v[162:165], v[198:201], v[44:47]
	v_mfma_f32_16x16x32_bf16 v[48:51], v[152:155], v[198:201], v[48:51]
	v_mfma_f32_16x16x32_bf16 v[48:51], v[148:151], v[190:193], v[48:51]
	v_mfma_f32_16x16x32_bf16 v[32:35], v[148:151], v[202:205], v[32:35]
	v_mfma_f32_16x16x32_bf16 v[32:35], v[152:155], v[210:213], v[32:35]
	v_mfma_f32_16x16x32_bf16 v[28:31], v[162:165], v[210:213], v[28:31]
	v_mfma_f32_16x16x32_bf16 v[28:31], v[158:161], v[202:205], v[28:31]
	v_mfma_f32_16x16x32_bf16 v[12:15], v[158:161], v[206:209], v[12:15]
	v_mfma_f32_16x16x32_bf16 v[12:15], v[162:165], v[214:217], v[12:15]
	v_mfma_f32_16x16x32_bf16 v[16:19], v[152:155], v[214:217], v[16:19]
	v_mfma_f32_16x16x32_bf16 v[16:19], v[148:151], v[206:209], v[16:19]
	v_mfma_f32_16x16x32_bf16 v[56:59], v[170:173], v[186:189], v[56:59]
	v_mfma_f32_16x16x32_bf16 v[56:59], v[174:177], v[194:197], v[56:59]
	v_mfma_f32_16x16x32_bf16 v[52:55], v[182:185], v[194:197], v[52:55]
	v_mfma_f32_16x16x32_bf16 v[52:55], v[178:181], v[186:189], v[52:55]
	v_mfma_f32_16x16x32_bf16 v[36:39], v[178:181], v[190:193], v[36:39]
	v_mfma_f32_16x16x32_bf16 v[36:39], v[182:185], v[198:201], v[36:39]
	v_mfma_f32_16x16x32_bf16 v[40:43], v[174:177], v[198:201], v[40:43]
	v_mfma_f32_16x16x32_bf16 v[40:43], v[170:173], v[190:193], v[40:43]
	v_mfma_f32_16x16x32_bf16 v[24:27], v[170:173], v[202:205], v[24:27]
	v_mfma_f32_16x16x32_bf16 v[24:27], v[174:177], v[210:213], v[24:27]
	v_mfma_f32_16x16x32_bf16 v[20:23], v[182:185], v[210:213], v[20:23]
	v_mfma_f32_16x16x32_bf16 v[20:23], v[178:181], v[202:205], v[20:23]
	v_mfma_f32_16x16x32_bf16 v[4:7], v[178:181], v[206:209], v[4:7]
	v_mfma_f32_16x16x32_bf16 v[4:7], v[182:185], v[214:217], v[4:7]
	v_mfma_f32_16x16x32_bf16 v[8:11], v[174:177], v[214:217], v[8:11]
	v_mfma_f32_16x16x32_bf16 v[8:11], v[170:173], v[206:209], v[8:11]
	s_barrier
	s_add_i32 s77, s77, 2
	s_add_u32 s56, s56, 0x100
	s_addc_u32 s57, s57, 0
	s_cmp_gt_u32 s77, 61
	s_cbranch_scc0 .LBB0_1371
	s_add_u32 s56, s53, 0xffffff00
	s_addc_u32 s57, s72, -1
	s_andn2_b64 vcc, exec, s[6:7]
	s_cbranch_vccnz .LBB0_1362
	v_mov_b32_e32 v4, 0
	s_mov_b32 s0, s48
	s_mov_b32 s8, s50
	s_mov_b64 s[18:19], s[54:55]
	s_mov_b32 s63, s52
	v_mov_b32_e32 v5, v4
	v_mov_b32_e32 v6, v4
	v_mov_b32_e32 v7, v4
	v_mov_b32_e32 v8, v4
	v_mov_b32_e32 v9, v4
	v_mov_b32_e32 v10, v4
	v_mov_b32_e32 v11, v4
	v_mov_b32_e32 v20, v4
	v_mov_b32_e32 v21, v4
	v_mov_b32_e32 v22, v4
	v_mov_b32_e32 v23, v4
	v_mov_b32_e32 v24, v4
	v_mov_b32_e32 v25, v4
	v_mov_b32_e32 v26, v4
	v_mov_b32_e32 v27, v4
	v_mov_b32_e32 v36, v4
	v_mov_b32_e32 v37, v4
	v_mov_b32_e32 v38, v4
	v_mov_b32_e32 v39, v4
	v_mov_b32_e32 v40, v4
	v_mov_b32_e32 v41, v4
	v_mov_b32_e32 v42, v4
	v_mov_b32_e32 v43, v4
	v_mov_b32_e32 v52, v4
	v_mov_b32_e32 v53, v4
	v_mov_b32_e32 v54, v4
	v_mov_b32_e32 v55, v4
	v_mov_b32_e32 v56, v4
	v_mov_b32_e32 v57, v4
	v_mov_b32_e32 v58, v4
	v_mov_b32_e32 v59, v4
	v_mov_b32_e32 v12, v4
	v_mov_b32_e32 v13, v4
	v_mov_b32_e32 v14, v4
	v_mov_b32_e32 v15, v4
	v_mov_b32_e32 v16, v4
	v_mov_b32_e32 v17, v4
	v_mov_b32_e32 v18, v4
	v_mov_b32_e32 v19, v4
	v_mov_b32_e32 v28, v4
	v_mov_b32_e32 v29, v4
	v_mov_b32_e32 v30, v4
	v_mov_b32_e32 v31, v4
	v_mov_b32_e32 v32, v4
	v_mov_b32_e32 v33, v4
	v_mov_b32_e32 v34, v4
	v_mov_b32_e32 v35, v4
	v_mov_b32_e32 v44, v4
	v_mov_b32_e32 v45, v4
	v_mov_b32_e32 v46, v4
	v_mov_b32_e32 v47, v4
	v_mov_b32_e32 v48, v4
	v_mov_b32_e32 v49, v4
	v_mov_b32_e32 v50, v4
	v_mov_b32_e32 v51, v4
	v_mov_b32_e32 v60, v4
	v_mov_b32_e32 v61, v4
	v_mov_b32_e32 v62, v4
	v_mov_b32_e32 v63, v4
	v_mov_b32_e32 v64, v4
	v_mov_b32_e32 v65, v4
	v_mov_b32_e32 v66, v4
	v_mov_b32_e32 v67, v4
	v_mov_b32_e32 v68, v4
	v_mov_b32_e32 v69, v4
	v_mov_b32_e32 v70, v4
	v_mov_b32_e32 v71, v4
	v_mov_b32_e32 v72, v4
	v_mov_b32_e32 v73, v4
	v_mov_b32_e32 v74, v4
	v_mov_b32_e32 v75, v4
	v_mov_b32_e32 v84, v4
	v_mov_b32_e32 v85, v4
	v_mov_b32_e32 v86, v4
	v_mov_b32_e32 v87, v4
	v_mov_b32_e32 v88, v4
	v_mov_b32_e32 v89, v4
	v_mov_b32_e32 v90, v4
	v_mov_b32_e32 v91, v4
	v_mov_b32_e32 v100, v4
	v_mov_b32_e32 v101, v4
	v_mov_b32_e32 v102, v4
	v_mov_b32_e32 v103, v4
	v_mov_b32_e32 v104, v4
	v_mov_b32_e32 v105, v4
	v_mov_b32_e32 v106, v4
	v_mov_b32_e32 v107, v4
	v_mov_b32_e32 v116, v4
	v_mov_b32_e32 v117, v4
	v_mov_b32_e32 v118, v4
	v_mov_b32_e32 v119, v4
	v_mov_b32_e32 v120, v4
	v_mov_b32_e32 v121, v4
	v_mov_b32_e32 v122, v4
	v_mov_b32_e32 v123, v4
	v_mov_b32_e32 v76, v4
	v_mov_b32_e32 v77, v4
	v_mov_b32_e32 v78, v4
	v_mov_b32_e32 v79, v4
	v_mov_b32_e32 v80, v4
	v_mov_b32_e32 v81, v4
	v_mov_b32_e32 v82, v4
	v_mov_b32_e32 v83, v4
	v_mov_b32_e32 v92, v4
	v_mov_b32_e32 v93, v4
	v_mov_b32_e32 v94, v4
	v_mov_b32_e32 v95, v4
	v_mov_b32_e32 v96, v4
	v_mov_b32_e32 v97, v4
	v_mov_b32_e32 v98, v4
	v_mov_b32_e32 v99, v4
	v_mov_b32_e32 v108, v4
	v_mov_b32_e32 v109, v4
	v_mov_b32_e32 v110, v4
	v_mov_b32_e32 v111, v4
	v_mov_b32_e32 v112, v4
	v_mov_b32_e32 v113, v4
	v_mov_b32_e32 v114, v4
	v_mov_b32_e32 v115, v4
	v_mov_b32_e32 v124, v4
	v_mov_b32_e32 v125, v4
	v_mov_b32_e32 v126, v4
	v_mov_b32_e32 v127, v4
	v_mov_b32_e32 v128, v4
	v_mov_b32_e32 v129, v4
	v_mov_b32_e32 v130, v4
	v_mov_b32_e32 v131, v4
	s_andn2_b64 vcc, exec, s[4:5]
	s_cbranch_vccnz .LBB0_1363
